# v31 + removed the redundant s_setprio 0 / s_setprio 1 pair between the two MFMA groups of every K-loop phase (priority stays raised across the phase)
# baseline (speedup 1.0000x reference)
; #define PG8_STAGE(bufoff, gbase, voff) do { _Pragma("unroll") for (int _i = 0; _i < 2; ++_i) \
;         __builtin_amdgcn_global_load_lds((const unsigned*)((const char*)(gbase) + (voff)[_i]), (LAS unsigned*)(lds + (bufoff) + ldsw + _i * 8192), 16, 0, PG8_AUX); } while (0)
; #define PG8_LDA(dst, b, h) do { _Pragma("unroll") for (int m = 0; m < 4; ++m) _Pragma("unroll") for (int k = 0; k < 2; ++k) dst[m][k] = *(const LAS bf16x8*)(lds + PG8_SA(b, h) + aoff + m * 2048 + k * 1024); } while (0)
; #define PG8_LDB(dst, b, h) do { _Pragma("unroll") for (int n = 0; n < 2; ++n) _Pragma("unroll") for (int k = 0; k < 2; ++k) dst[n][k] = *(const LAS bf16x8*)(lds + PG8_SB(b, h) + boff + n * 2048 + k * 1024); } while (0)
; #define PG8_MMA(ai, bj, At, Bt) do { __builtin_amdgcn_s_setprio(1); _Pragma("unroll") for (int m = 0; m < 4; ++m) _Pragma("unroll") for (int n = 0; n < 2; ++n) _Pragma("unroll") for (int k = 0; k < 2; ++k) \
;         acc[ai][bj][m][n] = __builtin_amdgcn_mfma_f32_16x16x32_bf16(Bt[n][k], At[m][k], acc[ai][bj][m][n], 0, 0, 0); __builtin_amdgcn_s_setprio(0); } while (0)
; #define PG8_WAIT_V(n) asm volatile("s_waitcnt vmcnt(" #n ")" ::: "memory")
; #define PG8_WAIT_L(n) asm volatile("s_waitcnt lgkmcnt(" #n ")" ::: "memory")
; #define PG8_BAR __builtin_amdgcn_s_barrier()
; #define PG8_SCHED __builtin_amdgcn_sched_barrier(0)
; template <class Epi, class Sched>
; __device__ __forceinline__ void gemm_phase(LAS unsigned char* lds, const Gemm g, const Sched& S, const Epi& E) {
;     ...
;         for (int t = 0; t < nt; t += 2) {
;             const bool last = (t == nt - 2);
;             const char* a1 = cA + (size_t)(t + 1) * kstep;
;             const char* a2 = last ? nA : cA + (size_t)(t + 2) * kstep; const char* b2 = last ? nB : cB + (size_t)(t + 2) * kstep;
;             const char* a3 = a2 + kstep; const char* b3 = b2 + kstep;
;     ...
;             PG8_LDB(B0, 0, 0); PG8_LDB(B1, 0, 1); PG8_SCHED; PG8_LDA(At, 0, 0); PG8_STAGE(PG8_SA(1, 1), a1 + hstepA, voffA);
;             PG8_WAIT_V(8); PG8_WAIT_L(0); PG8_BAR; PG8_MMA(0, 0, At, B0); PG8_MMA(0, 1, At, B1); PG8_BAR; PG8_SCHED;
;             PG8_LDA(At, 0, 1); PG8_STAGE(PG8_SB(0, 0), b2, voffB); PG8_STAGE(PG8_SB(0, 1), b2 + hstepB, voffB); PG8_STAGE(PG8_SA(0, 0), a2, voffA);
;             PG8_WAIT_V(8); PG8_WAIT_L(0); PG8_BAR; PG8_MMA(1, 0, At, B0); PG8_MMA(1, 1, At, B1); PG8_BAR; PG8_SCHED;
.LBB0_98:
	s_add_u32 s4, s22, 0xfff80080
	s_addc_u32 s54, s23, -1
	s_add_i32 s78, 0, 0x10000
	s_cmp_eq_u32 s94, 28
	s_cselect_b32 s57, s27, s54
	s_cselect_b32 s56, s47, s4
	v_add_u32_e32 v172, s78, v165
	s_cselect_b32 s55, s49, s92
	s_cselect_b32 s54, s61, s65
	s_add_i32 s4, 0, 0x14000
	ds_read_b128 v[156:159], v172
	ds_read_b128 v[160:163], v172 offset:1024
	ds_read_b128 v[168:171], v172 offset:2048
	ds_read_b128 v[182:185], v172 offset:3072
	v_add_u32_e32 v172, s4, v165
	ds_read_b128 v[186:189], v172
	ds_read_b128 v[194:197], v172 offset:1024
	ds_read_b128 v[198:201], v172 offset:2048
	ds_read_b128 v[202:205], v172 offset:3072
	v_lshl_add_u64 v[172:173], s[22:23], 0, v[134:135]
	s_add_i32 m0, s30, 0xc000
	ds_read_b128 v[206:209], v167
	ds_read_b128 v[210:213], v167 offset:1024
	ds_read_b128 v[214:217], v167 offset:2048
	ds_read_b128 v[218:221], v167 offset:3072
	ds_read_b128 v[222:225], v167 offset:4096
	ds_read_b128 v[226:229], v167 offset:5120
	ds_read_b128 v[230:233], v167 offset:6144
	ds_read_b128 v[234:237], v167 offset:7168
	global_load_lds_dwordx4 v[172:173], off
	v_lshl_add_u64 v[172:173], s[22:23], 0, v[154:155]
	s_add_i32 m0, s30, 0xe000
	s_nop 0
	global_load_lds_dwordx4 v[172:173], off
	s_waitcnt vmcnt(8)
	s_waitcnt lgkmcnt(0)
	s_barrier
	s_setprio 1
	s_waitcnt lgkmcnt(0)
	v_mfma_f32_16x16x32_bf16 v[124:127], v[156:159], v[206:209], v[124:127]
	v_mfma_f32_16x16x32_bf16 v[120:123], v[168:171], v[206:209], v[120:123]
	v_mfma_f32_16x16x32_bf16 v[108:111], v[156:159], v[214:217], v[108:111]
	v_mfma_f32_16x16x32_bf16 v[104:107], v[168:171], v[214:217], v[104:107]
	v_mfma_f32_16x16x32_bf16 v[92:95], v[156:159], v[222:225], v[92:95]
	v_mfma_f32_16x16x32_bf16 v[88:91], v[168:171], v[222:225], v[88:91]
	v_mfma_f32_16x16x32_bf16 v[76:79], v[156:159], v[230:233], v[76:79]
	v_mfma_f32_16x16x32_bf16 v[72:75], v[168:171], v[230:233], v[72:75]
	v_mfma_f32_16x16x32_bf16 v[124:127], v[160:163], v[210:213], v[124:127]
	v_mfma_f32_16x16x32_bf16 v[120:123], v[182:185], v[210:213], v[120:123]
	v_mfma_f32_16x16x32_bf16 v[108:111], v[160:163], v[218:221], v[108:111]
	v_mfma_f32_16x16x32_bf16 v[104:107], v[182:185], v[218:221], v[104:107]
	v_mfma_f32_16x16x32_bf16 v[92:95], v[160:163], v[226:229], v[92:95]
	v_mfma_f32_16x16x32_bf16 v[88:91], v[182:185], v[226:229], v[88:91]
	v_mfma_f32_16x16x32_bf16 v[76:79], v[160:163], v[234:237], v[76:79]
	v_mfma_f32_16x16x32_bf16 v[72:75], v[182:185], v[234:237], v[72:75]
	v_mfma_f32_16x16x32_bf16 v[116:119], v[186:189], v[206:209], v[116:119]
	v_mfma_f32_16x16x32_bf16 v[112:115], v[198:201], v[206:209], v[112:115]
	v_mfma_f32_16x16x32_bf16 v[100:103], v[186:189], v[214:217], v[100:103]
	v_mfma_f32_16x16x32_bf16 v[96:99], v[198:201], v[214:217], v[96:99]
	v_mfma_f32_16x16x32_bf16 v[84:87], v[186:189], v[222:225], v[84:87]
	v_mfma_f32_16x16x32_bf16 v[80:83], v[198:201], v[222:225], v[80:83]
	v_mfma_f32_16x16x32_bf16 v[68:71], v[186:189], v[230:233], v[68:71]
	v_mfma_f32_16x16x32_bf16 v[64:67], v[198:201], v[230:233], v[64:67]
	v_mfma_f32_16x16x32_bf16 v[116:119], v[194:197], v[210:213], v[116:119]
	v_mfma_f32_16x16x32_bf16 v[112:115], v[202:205], v[210:213], v[112:115]
	v_mfma_f32_16x16x32_bf16 v[100:103], v[194:197], v[218:221], v[100:103]
	v_mfma_f32_16x16x32_bf16 v[96:99], v[202:205], v[218:221], v[96:99]
	v_mfma_f32_16x16x32_bf16 v[84:87], v[194:197], v[226:229], v[84:87]
	v_mfma_f32_16x16x32_bf16 v[80:83], v[202:205], v[226:229], v[80:83]
	v_mfma_f32_16x16x32_bf16 v[68:71], v[194:197], v[234:237], v[68:71]
	v_mfma_f32_16x16x32_bf16 v[64:67], v[202:205], v[234:237], v[64:67]
	s_setprio 0
	s_barrier
	s_add_i32 s78, s78, s28
	v_lshl_add_u64 v[172:173], s[54:55], 0, v[136:137]
	s_mov_b32 m0, s78
	ds_read_b128 v[206:209], v167 offset:16384
	ds_read_b128 v[210:213], v167 offset:17408
	ds_read_b128 v[214:217], v167 offset:18432
	ds_read_b128 v[218:221], v167 offset:19456
	ds_read_b128 v[222:225], v167 offset:20480
	ds_read_b128 v[226:229], v167 offset:21504
	ds_read_b128 v[230:233], v167 offset:22528
	ds_read_b128 v[234:237], v167 offset:23552
	global_load_lds_dwordx4 v[172:173], off
	s_add_i32 m0, s78, 0x2000
	s_add_u32 s78, s54, 0x80000
	v_lshl_add_u64 v[190:191], s[54:55], 0, v[128:129]
	s_addc_u32 s79, s55, 0
	s_add_i32 s4, s4, s28
	global_load_lds_dwordx4 v[190:191], off
	v_lshl_add_u64 v[238:239], s[78:79], 0, v[136:137]
	s_mov_b32 m0, s4
	v_lshl_add_u64 v[240:241], s[56:57], 0, v[130:131]
	global_load_lds_dwordx4 v[238:239], off
	v_lshl_add_u64 v[238:239], s[78:79], 0, v[128:129]
	s_add_i32 m0, s4, 0x2000
	s_nop 0
	global_load_lds_dwordx4 v[238:239], off
	v_lshl_add_u64 v[238:239], s[56:57], 0, v[132:133]
	s_mov_b32 m0, s30
	s_nop 0
	global_load_lds_dwordx4 v[238:239], off
	s_mov_b32 m0, s34
	s_nop 0
	global_load_lds_dwordx4 v[240:241], off
	s_waitcnt vmcnt(8)
	s_waitcnt lgkmcnt(0)
	s_barrier
; #define PG8_STAGE(bufoff, gbase, voff) do { _Pragma("unroll") for (int _i = 0; _i < 2; ++_i) \
;         __builtin_amdgcn_global_load_lds((const unsigned*)((const char*)(gbase) + (voff)[_i]), (LAS unsigned*)(lds + (bufoff) + ldsw + _i * 8192), 16, 0, PG8_AUX); } while (0)
; #define PG8_LDA(dst, b, h) do { _Pragma("unroll") for (int m = 0; m < 4; ++m) _Pragma("unroll") for (int k = 0; k < 2; ++k) dst[m][k] = *(const LAS bf16x8*)(lds + PG8_SA(b, h) + aoff + m * 2048 + k * 1024); } while (0)
; #define PG8_LDB(dst, b, h) do { _Pragma("unroll") for (int n = 0; n < 2; ++n) _Pragma("unroll") for (int k = 0; k < 2; ++k) dst[n][k] = *(const LAS bf16x8*)(lds + PG8_SB(b, h) + boff + n * 2048 + k * 1024); } while (0)
; #define PG8_MMA(ai, bj, At, Bt) do { __builtin_amdgcn_s_setprio(1); _Pragma("unroll") for (int m = 0; m < 4; ++m) _Pragma("unroll") for (int n = 0; n < 2; ++n) _Pragma("unroll") for (int k = 0; k < 2; ++k) \
;         acc[ai][bj][m][n] = __builtin_amdgcn_mfma_f32_16x16x32_bf16(Bt[n][k], At[m][k], acc[ai][bj][m][n], 0, 0, 0); __builtin_amdgcn_s_setprio(0); } while (0)
; #define PG8_WAIT_V(n) asm volatile("s_waitcnt vmcnt(" #n ")" ::: "memory")
; #define PG8_WAIT_L(n) asm volatile("s_waitcnt lgkmcnt(" #n ")" ::: "memory")
; #define PG8_BAR __builtin_amdgcn_s_barrier()
; #define PG8_SCHED __builtin_amdgcn_sched_barrier(0)
; template <class Epi, class Sched>
; __device__ __forceinline__ void gemm_phase(LAS unsigned char* lds, const Gemm g, const Sched& S, const Epi& E) {
;     ...
;             PG8_WAIT_V(8); PG8_WAIT_L(0); PG8_BAR; PG8_MMA(1, 0, At, B0); PG8_MMA(1, 1, At, B1); PG8_BAR; PG8_SCHED;
;             PG8_LDB(B0, 1, 0); PG8_LDB(B1, 1, 1); PG8_SCHED; PG8_LDA(At, 1, 0); PG8_STAGE(PG8_SA(0, 1), a2 + hstepA, voffA);
;             PG8_WAIT_V(8); PG8_WAIT_L(0); PG8_BAR; PG8_MMA(0, 0, At, B0); PG8_MMA(0, 1, At, B1); PG8_BAR; PG8_SCHED;
	s_setprio 1
	s_waitcnt lgkmcnt(0)
	v_mfma_f32_16x16x32_bf16 v[60:63], v[156:159], v[206:209], v[60:63]
	v_mfma_f32_16x16x32_bf16 v[56:59], v[168:171], v[206:209], v[56:59]
	v_mfma_f32_16x16x32_bf16 v[44:47], v[156:159], v[214:217], v[44:47]
	v_mfma_f32_16x16x32_bf16 v[40:43], v[168:171], v[214:217], v[40:43]
	v_mfma_f32_16x16x32_bf16 v[28:31], v[156:159], v[222:225], v[28:31]
	v_mfma_f32_16x16x32_bf16 v[24:27], v[168:171], v[222:225], v[24:27]
	v_mfma_f32_16x16x32_bf16 v[12:15], v[156:159], v[230:233], v[12:15]
	v_mfma_f32_16x16x32_bf16 v[8:11], v[168:171], v[230:233], v[8:11]
	v_mfma_f32_16x16x32_bf16 v[60:63], v[160:163], v[210:213], v[60:63]
	v_mfma_f32_16x16x32_bf16 v[56:59], v[182:185], v[210:213], v[56:59]
	v_mfma_f32_16x16x32_bf16 v[44:47], v[160:163], v[218:221], v[44:47]
	v_mfma_f32_16x16x32_bf16 v[40:43], v[182:185], v[218:221], v[40:43]
	v_mfma_f32_16x16x32_bf16 v[28:31], v[160:163], v[226:229], v[28:31]
	v_mfma_f32_16x16x32_bf16 v[24:27], v[182:185], v[226:229], v[24:27]
	v_mfma_f32_16x16x32_bf16 v[12:15], v[160:163], v[234:237], v[12:15]
	v_mfma_f32_16x16x32_bf16 v[8:11], v[182:185], v[234:237], v[8:11]
	v_mfma_f32_16x16x32_bf16 v[52:55], v[186:189], v[206:209], v[52:55]
	v_mfma_f32_16x16x32_bf16 v[48:51], v[198:201], v[206:209], v[48:51]
	v_mfma_f32_16x16x32_bf16 v[36:39], v[186:189], v[214:217], v[36:39]
	v_mfma_f32_16x16x32_bf16 v[32:35], v[198:201], v[214:217], v[32:35]
	v_mfma_f32_16x16x32_bf16 v[20:23], v[186:189], v[222:225], v[20:23]
	v_mfma_f32_16x16x32_bf16 v[16:19], v[198:201], v[222:225], v[16:19]
	v_mfma_f32_16x16x32_bf16 v[4:7], v[186:189], v[230:233], v[4:7]
	v_mfma_f32_16x16x32_bf16 v[0:3], v[198:201], v[230:233], v[0:3]
	v_mfma_f32_16x16x32_bf16 v[52:55], v[194:197], v[210:213], v[52:55]
	v_mfma_f32_16x16x32_bf16 v[48:51], v[202:205], v[210:213], v[48:51]
	v_mfma_f32_16x16x32_bf16 v[36:39], v[194:197], v[218:221], v[36:39]
	v_mfma_f32_16x16x32_bf16 v[32:35], v[202:205], v[218:221], v[32:35]
	v_mfma_f32_16x16x32_bf16 v[20:23], v[194:197], v[226:229], v[20:23]
	v_mfma_f32_16x16x32_bf16 v[16:19], v[202:205], v[226:229], v[16:19]
	v_mfma_f32_16x16x32_bf16 v[4:7], v[194:197], v[234:237], v[4:7]
	v_mfma_f32_16x16x32_bf16 v[0:3], v[202:205], v[234:237], v[0:3]
	s_setprio 0
	s_barrier
	s_add_i32 s4, 0, 0x18000
	v_add_u32_e32 v181, s4, v165
	s_add_i32 s78, 0, 0x1c000
	ds_read_b128 v[156:159], v181
	ds_read_b128 v[160:163], v181 offset:1024
	ds_read_b128 v[168:171], v181 offset:2048
	ds_read_b128 v[182:185], v181 offset:3072
	v_add_u32_e32 v181, s78, v165
	ds_read_b128 v[186:189], v181
	ds_read_b128 v[194:197], v181 offset:1024
	ds_read_b128 v[198:201], v181 offset:2048
	ds_read_b128 v[202:205], v181 offset:3072
	s_add_u32 s56, s56, 0x80000
	s_addc_u32 s57, s57, 0
	s_mov_b32 m0, s36
	v_lshl_add_u64 v[242:243], s[56:57], 0, v[132:133]
	ds_read_b128 v[206:209], v167 offset:32768
	ds_read_b128 v[210:213], v167 offset:33792
	ds_read_b128 v[214:217], v167 offset:34816
	ds_read_b128 v[218:221], v167 offset:35840
	ds_read_b128 v[222:225], v167 offset:36864
	ds_read_b128 v[226:229], v167 offset:37888
	ds_read_b128 v[230:233], v167 offset:38912
	ds_read_b128 v[234:237], v167 offset:39936
	global_load_lds_dwordx4 v[242:243], off
	v_lshl_add_u64 v[242:243], s[56:57], 0, v[130:131]
	s_mov_b32 m0, s62
	s_nop 0
	global_load_lds_dwordx4 v[242:243], off
	s_waitcnt vmcnt(8)
	s_waitcnt lgkmcnt(0)
	s_barrier
	s_setprio 1
	s_waitcnt lgkmcnt(0)
	v_mfma_f32_16x16x32_bf16 v[124:127], v[156:159], v[206:209], v[124:127]
	v_mfma_f32_16x16x32_bf16 v[120:123], v[168:171], v[206:209], v[120:123]
	v_mfma_f32_16x16x32_bf16 v[108:111], v[156:159], v[214:217], v[108:111]
	v_mfma_f32_16x16x32_bf16 v[104:107], v[168:171], v[214:217], v[104:107]
	v_mfma_f32_16x16x32_bf16 v[92:95], v[156:159], v[222:225], v[92:95]
	v_mfma_f32_16x16x32_bf16 v[88:91], v[168:171], v[222:225], v[88:91]
	v_mfma_f32_16x16x32_bf16 v[76:79], v[156:159], v[230:233], v[76:79]
	v_mfma_f32_16x16x32_bf16 v[72:75], v[168:171], v[230:233], v[72:75]
	v_mfma_f32_16x16x32_bf16 v[124:127], v[160:163], v[210:213], v[124:127]
	v_mfma_f32_16x16x32_bf16 v[120:123], v[182:185], v[210:213], v[120:123]
	v_mfma_f32_16x16x32_bf16 v[108:111], v[160:163], v[218:221], v[108:111]
	v_mfma_f32_16x16x32_bf16 v[104:107], v[182:185], v[218:221], v[104:107]
	v_mfma_f32_16x16x32_bf16 v[92:95], v[160:163], v[226:229], v[92:95]
	v_mfma_f32_16x16x32_bf16 v[88:91], v[182:185], v[226:229], v[88:91]
	v_mfma_f32_16x16x32_bf16 v[76:79], v[160:163], v[234:237], v[76:79]
	v_mfma_f32_16x16x32_bf16 v[72:75], v[182:185], v[234:237], v[72:75]
	v_mfma_f32_16x16x32_bf16 v[116:119], v[186:189], v[206:209], v[116:119]
	v_mfma_f32_16x16x32_bf16 v[112:115], v[198:201], v[206:209], v[112:115]
	v_mfma_f32_16x16x32_bf16 v[100:103], v[186:189], v[214:217], v[100:103]
	v_mfma_f32_16x16x32_bf16 v[96:99], v[198:201], v[214:217], v[96:99]
	v_mfma_f32_16x16x32_bf16 v[84:87], v[186:189], v[222:225], v[84:87]
	v_mfma_f32_16x16x32_bf16 v[80:83], v[198:201], v[222:225], v[80:83]
	v_mfma_f32_16x16x32_bf16 v[68:71], v[186:189], v[230:233], v[68:71]
	v_mfma_f32_16x16x32_bf16 v[64:67], v[198:201], v[230:233], v[64:67]
	v_mfma_f32_16x16x32_bf16 v[116:119], v[194:197], v[210:213], v[116:119]
	v_mfma_f32_16x16x32_bf16 v[112:115], v[202:205], v[210:213], v[112:115]
	v_mfma_f32_16x16x32_bf16 v[100:103], v[194:197], v[218:221], v[100:103]
	v_mfma_f32_16x16x32_bf16 v[96:99], v[202:205], v[218:221], v[96:99]
	v_mfma_f32_16x16x32_bf16 v[84:87], v[194:197], v[226:229], v[84:87]
	v_mfma_f32_16x16x32_bf16 v[80:83], v[202:205], v[226:229], v[80:83]
	v_mfma_f32_16x16x32_bf16 v[68:71], v[194:197], v[234:237], v[68:71]
	v_mfma_f32_16x16x32_bf16 v[64:67], v[202:205], v[234:237], v[64:67]
	s_setprio 0
	s_barrier
; #define PG8_STAGE(bufoff, gbase, voff) do { _Pragma("unroll") for (int _i = 0; _i < 2; ++_i) \
;         __builtin_amdgcn_global_load_lds((const unsigned*)((const char*)(gbase) + (voff)[_i]), (LAS unsigned*)(lds + (bufoff) + ldsw + _i * 8192), 16, 0, PG8_AUX); } while (0)
; #define PG8_LDA(dst, b, h) do { _Pragma("unroll") for (int m = 0; m < 4; ++m) _Pragma("unroll") for (int k = 0; k < 2; ++k) dst[m][k] = *(const LAS bf16x8*)(lds + PG8_SA(b, h) + aoff + m * 2048 + k * 1024); } while (0)
; #define PG8_MMA(ai, bj, At, Bt) do { __builtin_amdgcn_s_setprio(1); _Pragma("unroll") for (int m = 0; m < 4; ++m) _Pragma("unroll") for (int n = 0; n < 2; ++n) _Pragma("unroll") for (int k = 0; k < 2; ++k) \
;         acc[ai][bj][m][n] = __builtin_amdgcn_mfma_f32_16x16x32_bf16(Bt[n][k], At[m][k], acc[ai][bj][m][n], 0, 0, 0); __builtin_amdgcn_s_setprio(0); } while (0)
; #define PG8_WAIT_V(n) asm volatile("s_waitcnt vmcnt(" #n ")" ::: "memory")
; #define PG8_WAIT_L(n) asm volatile("s_waitcnt lgkmcnt(" #n ")" ::: "memory")
; #define PG8_BAR __builtin_amdgcn_s_barrier()
; #define PG8_SCHED __builtin_amdgcn_sched_barrier(0)
; template <class Epi, class Sched>
; __device__ __forceinline__ void gemm_phase(LAS unsigned char* lds, const Gemm g, const Sched& S, const Epi& E) {
;     ...
;         for (int t = 0; t < nt; t += 2) {
;     ...
;             PG8_LDA(At, 1, 1); PG8_STAGE(PG8_SB(1, 0), b3, voffB); PG8_STAGE(PG8_SB(1, 1), b3 + hstepB, voffB); PG8_STAGE(PG8_SA(1, 0), a3, voffA);
;             PG8_WAIT_V(8); PG8_WAIT_L(0); PG8_BAR; PG8_MMA(1, 0, At, B0); PG8_MMA(1, 1, At, B1); PG8_BAR; PG8_SCHED;
	s_add_i32 s4, s4, s28
	v_lshl_add_u64 v[172:173], v[172:173], 0, s[12:13]
	s_mov_b32 m0, s4
	ds_read_b128 v[206:209], v167 offset:49152
	ds_read_b128 v[210:213], v167 offset:50176
	ds_read_b128 v[214:217], v167 offset:51200
	ds_read_b128 v[218:221], v167 offset:52224
	ds_read_b128 v[222:225], v167 offset:53248
	ds_read_b128 v[226:229], v167 offset:54272
	ds_read_b128 v[230:233], v167 offset:55296
	ds_read_b128 v[234:237], v167 offset:56320
	global_load_lds_dwordx4 v[172:173], off
	s_add_i32 m0, s4, 0x2000
	s_add_u32 s54, s54, 0x80080
	v_lshl_add_u64 v[172:173], v[190:191], 0, s[12:13]
	s_addc_u32 s55, s55, 0
	s_add_i32 s4, s78, s28
	global_load_lds_dwordx4 v[172:173], off
	v_lshl_add_u64 v[172:173], s[54:55], 0, v[136:137]
	s_mov_b32 m0, s4
	s_nop 0
	global_load_lds_dwordx4 v[172:173], off
	v_lshl_add_u64 v[172:173], s[54:55], 0, v[128:129]
	s_add_i32 m0, s4, 0x2000
	s_nop 0
	global_load_lds_dwordx4 v[172:173], off
	v_lshl_add_u64 v[172:173], v[238:239], 0, s[12:13]
	s_mov_b32 m0, s63
	s_nop 0
	global_load_lds_dwordx4 v[172:173], off
	v_lshl_add_u64 v[172:173], v[240:241], 0, s[12:13]
	s_mov_b32 m0, s64
	s_nop 0
	global_load_lds_dwordx4 v[172:173], off
	s_waitcnt vmcnt(8)
	s_waitcnt lgkmcnt(0)
	s_barrier
	s_setprio 1
	s_waitcnt lgkmcnt(0)
	v_mfma_f32_16x16x32_bf16 v[60:63], v[156:159], v[206:209], v[60:63]
	v_mfma_f32_16x16x32_bf16 v[56:59], v[168:171], v[206:209], v[56:59]
	v_mfma_f32_16x16x32_bf16 v[44:47], v[156:159], v[214:217], v[44:47]
	v_mfma_f32_16x16x32_bf16 v[40:43], v[168:171], v[214:217], v[40:43]
	v_mfma_f32_16x16x32_bf16 v[28:31], v[156:159], v[222:225], v[28:31]
	v_mfma_f32_16x16x32_bf16 v[24:27], v[168:171], v[222:225], v[24:27]
	v_mfma_f32_16x16x32_bf16 v[12:15], v[156:159], v[230:233], v[12:15]
	v_mfma_f32_16x16x32_bf16 v[8:11], v[168:171], v[230:233], v[8:11]
	v_mfma_f32_16x16x32_bf16 v[60:63], v[160:163], v[210:213], v[60:63]
	v_mfma_f32_16x16x32_bf16 v[56:59], v[182:185], v[210:213], v[56:59]
	v_mfma_f32_16x16x32_bf16 v[44:47], v[160:163], v[218:221], v[44:47]
	v_mfma_f32_16x16x32_bf16 v[40:43], v[182:185], v[218:221], v[40:43]
	v_mfma_f32_16x16x32_bf16 v[28:31], v[160:163], v[226:229], v[28:31]
	v_mfma_f32_16x16x32_bf16 v[24:27], v[182:185], v[226:229], v[24:27]
	v_mfma_f32_16x16x32_bf16 v[12:15], v[160:163], v[234:237], v[12:15]
	v_mfma_f32_16x16x32_bf16 v[8:11], v[182:185], v[234:237], v[8:11]
	v_mfma_f32_16x16x32_bf16 v[52:55], v[186:189], v[206:209], v[52:55]
	v_mfma_f32_16x16x32_bf16 v[48:51], v[198:201], v[206:209], v[48:51]
	v_mfma_f32_16x16x32_bf16 v[36:39], v[186:189], v[214:217], v[36:39]
	v_mfma_f32_16x16x32_bf16 v[32:35], v[198:201], v[214:217], v[32:35]
	v_mfma_f32_16x16x32_bf16 v[20:23], v[186:189], v[222:225], v[20:23]
	v_mfma_f32_16x16x32_bf16 v[16:19], v[198:201], v[222:225], v[16:19]
	v_mfma_f32_16x16x32_bf16 v[4:7], v[186:189], v[230:233], v[4:7]
	v_mfma_f32_16x16x32_bf16 v[0:3], v[198:201], v[230:233], v[0:3]
	v_mfma_f32_16x16x32_bf16 v[52:55], v[194:197], v[210:213], v[52:55]
	v_mfma_f32_16x16x32_bf16 v[48:51], v[202:205], v[210:213], v[48:51]
	v_mfma_f32_16x16x32_bf16 v[36:39], v[194:197], v[218:221], v[36:39]
	v_mfma_f32_16x16x32_bf16 v[32:35], v[202:205], v[218:221], v[32:35]
	v_mfma_f32_16x16x32_bf16 v[20:23], v[194:197], v[226:229], v[20:23]
	v_mfma_f32_16x16x32_bf16 v[16:19], v[202:205], v[226:229], v[16:19]
	v_mfma_f32_16x16x32_bf16 v[4:7], v[194:197], v[234:237], v[4:7]
	v_mfma_f32_16x16x32_bf16 v[0:3], v[202:205], v[234:237], v[0:3]
	s_setprio 0
	s_barrier
	s_add_i32 s94, s94, 2
	s_add_u32 s22, s22, 0x100
	s_addc_u32 s23, s23, 0
	s_add_u32 s65, s65, 0x100
	s_addc_u32 s92, s92, 0
	s_cmp_gt_u32 s94, 29
	s_cbranch_scc0 .LBB0_98
	s_and_b64 vcc, exec, s[44:45]
	s_cbranch_vccz .LBB0_101
	s_barrier

; #define PG8_STAGE(bufoff, gbase, voff) do { _Pragma("unroll") for (int _i = 0; _i < 2; ++_i) \
;         __builtin_amdgcn_global_load_lds((const unsigned*)((const char*)(gbase) + (voff)[_i]), (LAS unsigned*)(lds + (bufoff) + ldsw + _i * 8192), 16, 0, PG8_AUX); } while (0)
; #define PG8_LDA(dst, b, h) do { _Pragma("unroll") for (int m = 0; m < 4; ++m) _Pragma("unroll") for (int k = 0; k < 2; ++k) dst[m][k] = *(const LAS bf16x8*)(lds + PG8_SA(b, h) + aoff + m * 2048 + k * 1024); } while (0)
; #define PG8_LDB(dst, b, h) do { _Pragma("unroll") for (int n = 0; n < 2; ++n) _Pragma("unroll") for (int k = 0; k < 2; ++k) dst[n][k] = *(const LAS bf16x8*)(lds + PG8_SB(b, h) + boff + n * 2048 + k * 1024); } while (0)
; #define PG8_MMA(ai, bj, At, Bt) do { __builtin_amdgcn_s_setprio(1); _Pragma("unroll") for (int m = 0; m < 4; ++m) _Pragma("unroll") for (int n = 0; n < 2; ++n) _Pragma("unroll") for (int k = 0; k < 2; ++k) \
;         acc[ai][bj][m][n] = __builtin_amdgcn_mfma_f32_16x16x32_bf16(Bt[n][k], At[m][k], acc[ai][bj][m][n], 0, 0, 0); __builtin_amdgcn_s_setprio(0); } while (0)
; #define PG8_WAIT_V(n) asm volatile("s_waitcnt vmcnt(" #n ")" ::: "memory")
; #define PG8_WAIT_L(n) asm volatile("s_waitcnt lgkmcnt(" #n ")" ::: "memory")
; #define PG8_BAR __builtin_amdgcn_s_barrier()
; #define PG8_SCHED __builtin_amdgcn_sched_barrier(0)
; template <class Epi, class Sched>
; __device__ __forceinline__ void gemm_phase(LAS unsigned char* lds, const Gemm g, const Sched& S, const Epi& E) {
;     ...
;         for (int t = 0; t < nt; t += 2) {
;             const bool last = (t == nt - 2);
;             const char* a1 = cA + (size_t)(t + 1) * kstep;
;             const char* a2 = last ? nA : cA + (size_t)(t + 2) * kstep; const char* b2 = last ? nB : cB + (size_t)(t + 2) * kstep;
;             const char* a3 = a2 + kstep; const char* b3 = b2 + kstep;
;     ...
;             PG8_LDB(B0, 0, 0); PG8_LDB(B1, 0, 1); PG8_SCHED; PG8_LDA(At, 0, 0); PG8_STAGE(PG8_SA(1, 1), a1 + hstepA, voffA);
;             PG8_WAIT_V(8); PG8_WAIT_L(0); PG8_BAR; PG8_MMA(0, 0, At, B0); PG8_MMA(0, 1, At, B1); PG8_BAR; PG8_SCHED;
;             PG8_LDA(At, 0, 1); PG8_STAGE(PG8_SB(0, 0), b2, voffB); PG8_STAGE(PG8_SB(0, 1), b2 + hstepB, voffB); PG8_STAGE(PG8_SA(0, 0), a2, voffA);
;             PG8_WAIT_V(8); PG8_WAIT_L(0); PG8_BAR; PG8_MMA(1, 0, At, B0); PG8_MMA(1, 1, At, B1); PG8_BAR; PG8_SCHED;
.LBB0_141:
	s_add_i32 s49, s4, 2
	s_add_u32 s40, s22, 0xfff80080
	s_addc_u32 s41, s23, -1
	s_add_i32 s65, 0, 0x10000
	s_cmp_eq_u32 s20, s4
	s_cselect_b32 s53, s1, s41
	s_cselect_b32 s52, s0, s40
	s_cselect_b32 s41, s51, s47
	s_cselect_b32 s40, s50, s27
	s_add_i32 s4, 0, 0x14000
	v_add_u32_e32 v168, s65, v173
	v_add_u32_e32 v183, s4, v173
	ds_read_b128 v[128:131], v168
	ds_read_b128 v[132:135], v168 offset:1024
	ds_read_b128 v[164:167], v168 offset:2048
	ds_read_b128 v[168:171], v168 offset:3072
	ds_read_b128 v[184:187], v183
	ds_read_b128 v[188:191], v183 offset:1024
	ds_read_b128 v[194:197], v183 offset:2048
	ds_read_b128 v[198:201], v183 offset:3072
	v_lshl_add_u64 v[234:235], s[22:23], 0, v[160:161]
	s_add_i32 m0, s30, 0xc000
	ds_read_b128 v[202:205], v182
	ds_read_b128 v[206:209], v182 offset:1024
	ds_read_b128 v[210:213], v182 offset:2048
	ds_read_b128 v[214:217], v182 offset:3072
	ds_read_b128 v[218:221], v182 offset:4096
	ds_read_b128 v[222:225], v182 offset:5120
	ds_read_b128 v[226:229], v182 offset:6144
	ds_read_b128 v[230:233], v182 offset:7168
	global_load_lds_dwordx4 v[234:235], off
	v_lshl_add_u64 v[234:235], s[22:23], 0, v[162:163]
	s_add_i32 m0, s30, 0xe000
	s_nop 0
	global_load_lds_dwordx4 v[234:235], off
	s_waitcnt vmcnt(8)
	s_waitcnt lgkmcnt(0)
	s_barrier
	s_setprio 1
	s_waitcnt lgkmcnt(0)
	v_mfma_f32_16x16x32_bf16 v[124:127], v[128:131], v[202:205], v[124:127]
	v_mfma_f32_16x16x32_bf16 v[120:123], v[164:167], v[202:205], v[120:123]
	v_mfma_f32_16x16x32_bf16 v[108:111], v[128:131], v[210:213], v[108:111]
	v_mfma_f32_16x16x32_bf16 v[104:107], v[164:167], v[210:213], v[104:107]
	v_mfma_f32_16x16x32_bf16 v[92:95], v[128:131], v[218:221], v[92:95]
	v_mfma_f32_16x16x32_bf16 v[88:91], v[164:167], v[218:221], v[88:91]
	v_mfma_f32_16x16x32_bf16 v[76:79], v[128:131], v[226:229], v[76:79]
	v_mfma_f32_16x16x32_bf16 v[72:75], v[164:167], v[226:229], v[72:75]
	v_mfma_f32_16x16x32_bf16 v[124:127], v[132:135], v[206:209], v[124:127]
	v_mfma_f32_16x16x32_bf16 v[120:123], v[168:171], v[206:209], v[120:123]
	v_mfma_f32_16x16x32_bf16 v[108:111], v[132:135], v[214:217], v[108:111]
	v_mfma_f32_16x16x32_bf16 v[104:107], v[168:171], v[214:217], v[104:107]
	v_mfma_f32_16x16x32_bf16 v[92:95], v[132:135], v[222:225], v[92:95]
	v_mfma_f32_16x16x32_bf16 v[88:91], v[168:171], v[222:225], v[88:91]
	v_mfma_f32_16x16x32_bf16 v[76:79], v[132:135], v[230:233], v[76:79]
	v_mfma_f32_16x16x32_bf16 v[72:75], v[168:171], v[230:233], v[72:75]
	v_mfma_f32_16x16x32_bf16 v[116:119], v[184:187], v[202:205], v[116:119]
	v_mfma_f32_16x16x32_bf16 v[112:115], v[194:197], v[202:205], v[112:115]
	v_mfma_f32_16x16x32_bf16 v[100:103], v[184:187], v[210:213], v[100:103]
	v_mfma_f32_16x16x32_bf16 v[96:99], v[194:197], v[210:213], v[96:99]
	v_mfma_f32_16x16x32_bf16 v[84:87], v[184:187], v[218:221], v[84:87]
	v_mfma_f32_16x16x32_bf16 v[80:83], v[194:197], v[218:221], v[80:83]
	v_mfma_f32_16x16x32_bf16 v[68:71], v[184:187], v[226:229], v[68:71]
	v_mfma_f32_16x16x32_bf16 v[64:67], v[194:197], v[226:229], v[64:67]
	v_mfma_f32_16x16x32_bf16 v[116:119], v[188:191], v[206:209], v[116:119]
	v_mfma_f32_16x16x32_bf16 v[112:115], v[198:201], v[206:209], v[112:115]
	v_mfma_f32_16x16x32_bf16 v[100:103], v[188:191], v[214:217], v[100:103]
	v_mfma_f32_16x16x32_bf16 v[96:99], v[198:201], v[214:217], v[96:99]
	v_mfma_f32_16x16x32_bf16 v[84:87], v[188:191], v[222:225], v[84:87]
	v_mfma_f32_16x16x32_bf16 v[80:83], v[198:201], v[222:225], v[80:83]
	v_mfma_f32_16x16x32_bf16 v[68:71], v[188:191], v[230:233], v[68:71]
	v_mfma_f32_16x16x32_bf16 v[64:67], v[198:201], v[230:233], v[64:67]
	s_setprio 0
	s_barrier
	s_add_i32 s65, s65, s28
	v_lshl_add_u64 v[234:235], s[40:41], 0, v[136:137]
	s_mov_b32 m0, s65
	ds_read_b128 v[202:205], v182 offset:16384
	ds_read_b128 v[206:209], v182 offset:17408
	ds_read_b128 v[210:213], v182 offset:18432
	ds_read_b128 v[214:217], v182 offset:19456
	ds_read_b128 v[218:221], v182 offset:20480
	ds_read_b128 v[222:225], v182 offset:21504
	ds_read_b128 v[226:229], v182 offset:22528
	ds_read_b128 v[230:233], v182 offset:23552
	global_load_lds_dwordx4 v[234:235], off
	s_add_i32 m0, s65, 0x2000
	s_add_u32 s78, s40, 0x80000
	v_lshl_add_u64 v[236:237], s[40:41], 0, v[154:155]
	s_addc_u32 s79, s41, 0
	s_add_i32 s4, s4, s28
	global_load_lds_dwordx4 v[236:237], off
	v_lshl_add_u64 v[238:239], s[78:79], 0, v[136:137]
	s_mov_b32 m0, s4
	v_lshl_add_u64 v[240:241], s[52:53], 0, v[156:157]
	global_load_lds_dwordx4 v[238:239], off
	v_lshl_add_u64 v[238:239], s[78:79], 0, v[154:155]
	s_add_i32 m0, s4, 0x2000
	s_nop 0
	global_load_lds_dwordx4 v[238:239], off
	v_lshl_add_u64 v[238:239], s[52:53], 0, v[158:159]
	s_mov_b32 m0, s30
	s_nop 0
	global_load_lds_dwordx4 v[238:239], off
	s_mov_b32 m0, s34
	s_nop 0
	global_load_lds_dwordx4 v[240:241], off
	s_waitcnt vmcnt(8)
	s_waitcnt lgkmcnt(0)
	s_barrier
; #define PG8_STAGE(bufoff, gbase, voff) do { _Pragma("unroll") for (int _i = 0; _i < 2; ++_i) \
;         __builtin_amdgcn_global_load_lds((const unsigned*)((const char*)(gbase) + (voff)[_i]), (LAS unsigned*)(lds + (bufoff) + ldsw + _i * 8192), 16, 0, PG8_AUX); } while (0)
; #define PG8_LDA(dst, b, h) do { _Pragma("unroll") for (int m = 0; m < 4; ++m) _Pragma("unroll") for (int k = 0; k < 2; ++k) dst[m][k] = *(const LAS bf16x8*)(lds + PG8_SA(b, h) + aoff + m * 2048 + k * 1024); } while (0)
; #define PG8_LDB(dst, b, h) do { _Pragma("unroll") for (int n = 0; n < 2; ++n) _Pragma("unroll") for (int k = 0; k < 2; ++k) dst[n][k] = *(const LAS bf16x8*)(lds + PG8_SB(b, h) + boff + n * 2048 + k * 1024); } while (0)
; #define PG8_MMA(ai, bj, At, Bt) do { __builtin_amdgcn_s_setprio(1); _Pragma("unroll") for (int m = 0; m < 4; ++m) _Pragma("unroll") for (int n = 0; n < 2; ++n) _Pragma("unroll") for (int k = 0; k < 2; ++k) \
;         acc[ai][bj][m][n] = __builtin_amdgcn_mfma_f32_16x16x32_bf16(Bt[n][k], At[m][k], acc[ai][bj][m][n], 0, 0, 0); __builtin_amdgcn_s_setprio(0); } while (0)
; #define PG8_WAIT_V(n) asm volatile("s_waitcnt vmcnt(" #n ")" ::: "memory")
; #define PG8_WAIT_L(n) asm volatile("s_waitcnt lgkmcnt(" #n ")" ::: "memory")
; #define PG8_BAR __builtin_amdgcn_s_barrier()
; #define PG8_SCHED __builtin_amdgcn_sched_barrier(0)
; template <class Epi, class Sched>
; __device__ __forceinline__ void gemm_phase(LAS unsigned char* lds, const Gemm g, const Sched& S, const Epi& E) {
;     ...
;             PG8_WAIT_V(8); PG8_WAIT_L(0); PG8_BAR; PG8_MMA(1, 0, At, B0); PG8_MMA(1, 1, At, B1); PG8_BAR; PG8_SCHED;
;             PG8_LDB(B0, 1, 0); PG8_LDB(B1, 1, 1); PG8_SCHED; PG8_LDA(At, 1, 0); PG8_STAGE(PG8_SA(0, 1), a2 + hstepA, voffA);
;             PG8_WAIT_V(8); PG8_WAIT_L(0); PG8_BAR; PG8_MMA(0, 0, At, B0); PG8_MMA(0, 1, At, B1); PG8_BAR; PG8_SCHED;
	s_setprio 1
	s_waitcnt lgkmcnt(0)
	v_mfma_f32_16x16x32_bf16 v[60:63], v[128:131], v[202:205], v[60:63]
	v_mfma_f32_16x16x32_bf16 v[56:59], v[164:167], v[202:205], v[56:59]
	v_mfma_f32_16x16x32_bf16 v[44:47], v[128:131], v[210:213], v[44:47]
	v_mfma_f32_16x16x32_bf16 v[40:43], v[164:167], v[210:213], v[40:43]
	v_mfma_f32_16x16x32_bf16 v[28:31], v[128:131], v[218:221], v[28:31]
	v_mfma_f32_16x16x32_bf16 v[24:27], v[164:167], v[218:221], v[24:27]
	v_mfma_f32_16x16x32_bf16 v[12:15], v[128:131], v[226:229], v[12:15]
	v_mfma_f32_16x16x32_bf16 v[8:11], v[164:167], v[226:229], v[8:11]
	v_mfma_f32_16x16x32_bf16 v[60:63], v[132:135], v[206:209], v[60:63]
	v_mfma_f32_16x16x32_bf16 v[56:59], v[168:171], v[206:209], v[56:59]
	v_mfma_f32_16x16x32_bf16 v[44:47], v[132:135], v[214:217], v[44:47]
	v_mfma_f32_16x16x32_bf16 v[40:43], v[168:171], v[214:217], v[40:43]
	v_mfma_f32_16x16x32_bf16 v[28:31], v[132:135], v[222:225], v[28:31]
	v_mfma_f32_16x16x32_bf16 v[24:27], v[168:171], v[222:225], v[24:27]
	v_mfma_f32_16x16x32_bf16 v[12:15], v[132:135], v[230:233], v[12:15]
	v_mfma_f32_16x16x32_bf16 v[8:11], v[168:171], v[230:233], v[8:11]
	v_mfma_f32_16x16x32_bf16 v[52:55], v[184:187], v[202:205], v[52:55]
	v_mfma_f32_16x16x32_bf16 v[48:51], v[194:197], v[202:205], v[48:51]
	v_mfma_f32_16x16x32_bf16 v[36:39], v[184:187], v[210:213], v[36:39]
	v_mfma_f32_16x16x32_bf16 v[32:35], v[194:197], v[210:213], v[32:35]
	v_mfma_f32_16x16x32_bf16 v[20:23], v[184:187], v[218:221], v[20:23]
	v_mfma_f32_16x16x32_bf16 v[16:19], v[194:197], v[218:221], v[16:19]
	v_mfma_f32_16x16x32_bf16 v[4:7], v[184:187], v[226:229], v[4:7]
	v_mfma_f32_16x16x32_bf16 v[0:3], v[194:197], v[226:229], v[0:3]
	v_mfma_f32_16x16x32_bf16 v[52:55], v[188:191], v[206:209], v[52:55]
	v_mfma_f32_16x16x32_bf16 v[48:51], v[198:201], v[206:209], v[48:51]
	v_mfma_f32_16x16x32_bf16 v[36:39], v[188:191], v[214:217], v[36:39]
	v_mfma_f32_16x16x32_bf16 v[32:35], v[198:201], v[214:217], v[32:35]
	v_mfma_f32_16x16x32_bf16 v[20:23], v[188:191], v[222:225], v[20:23]
	v_mfma_f32_16x16x32_bf16 v[16:19], v[198:201], v[222:225], v[16:19]
	v_mfma_f32_16x16x32_bf16 v[4:7], v[188:191], v[230:233], v[4:7]
	v_mfma_f32_16x16x32_bf16 v[0:3], v[198:201], v[230:233], v[0:3]
	s_setprio 0
	s_barrier
	s_add_i32 s4, 0, 0x18000
	s_add_i32 s65, 0, 0x1c000
	v_add_u32_e32 v168, s4, v173
	v_add_u32_e32 v183, s65, v173
	ds_read_b128 v[128:131], v168
	ds_read_b128 v[132:135], v168 offset:1024
	ds_read_b128 v[164:167], v168 offset:2048
	ds_read_b128 v[168:171], v168 offset:3072
	ds_read_b128 v[184:187], v183
	ds_read_b128 v[188:191], v183 offset:1024
	ds_read_b128 v[194:197], v183 offset:2048
	ds_read_b128 v[198:201], v183 offset:3072
	s_add_u32 s52, s52, 0x80000
	s_addc_u32 s53, s53, 0
	s_mov_b32 m0, s36
	v_lshl_add_u64 v[242:243], s[52:53], 0, v[158:159]
	ds_read_b128 v[202:205], v182 offset:32768
	ds_read_b128 v[206:209], v182 offset:33792
	ds_read_b128 v[210:213], v182 offset:34816
	ds_read_b128 v[214:217], v182 offset:35840
	ds_read_b128 v[218:221], v182 offset:36864
	ds_read_b128 v[222:225], v182 offset:37888
	ds_read_b128 v[226:229], v182 offset:38912
	ds_read_b128 v[230:233], v182 offset:39936
	global_load_lds_dwordx4 v[242:243], off
	v_lshl_add_u64 v[242:243], s[52:53], 0, v[156:157]
	s_mov_b32 m0, s54
	s_nop 0
	global_load_lds_dwordx4 v[242:243], off
	s_waitcnt vmcnt(8)
	s_waitcnt lgkmcnt(0)
	s_barrier
	s_setprio 1
	s_waitcnt lgkmcnt(0)
	v_mfma_f32_16x16x32_bf16 v[124:127], v[128:131], v[202:205], v[124:127]
	v_mfma_f32_16x16x32_bf16 v[120:123], v[164:167], v[202:205], v[120:123]
	v_mfma_f32_16x16x32_bf16 v[108:111], v[128:131], v[210:213], v[108:111]
	v_mfma_f32_16x16x32_bf16 v[104:107], v[164:167], v[210:213], v[104:107]
	v_mfma_f32_16x16x32_bf16 v[92:95], v[128:131], v[218:221], v[92:95]
	v_mfma_f32_16x16x32_bf16 v[88:91], v[164:167], v[218:221], v[88:91]
	v_mfma_f32_16x16x32_bf16 v[76:79], v[128:131], v[226:229], v[76:79]
	v_mfma_f32_16x16x32_bf16 v[72:75], v[164:167], v[226:229], v[72:75]
	v_mfma_f32_16x16x32_bf16 v[124:127], v[132:135], v[206:209], v[124:127]
	v_mfma_f32_16x16x32_bf16 v[120:123], v[168:171], v[206:209], v[120:123]
	v_mfma_f32_16x16x32_bf16 v[108:111], v[132:135], v[214:217], v[108:111]
	v_mfma_f32_16x16x32_bf16 v[104:107], v[168:171], v[214:217], v[104:107]
	v_mfma_f32_16x16x32_bf16 v[92:95], v[132:135], v[222:225], v[92:95]
	v_mfma_f32_16x16x32_bf16 v[88:91], v[168:171], v[222:225], v[88:91]
	v_mfma_f32_16x16x32_bf16 v[76:79], v[132:135], v[230:233], v[76:79]
	v_mfma_f32_16x16x32_bf16 v[72:75], v[168:171], v[230:233], v[72:75]
	v_mfma_f32_16x16x32_bf16 v[116:119], v[184:187], v[202:205], v[116:119]
	v_mfma_f32_16x16x32_bf16 v[112:115], v[194:197], v[202:205], v[112:115]
	v_mfma_f32_16x16x32_bf16 v[100:103], v[184:187], v[210:213], v[100:103]
	v_mfma_f32_16x16x32_bf16 v[96:99], v[194:197], v[210:213], v[96:99]
	v_mfma_f32_16x16x32_bf16 v[84:87], v[184:187], v[218:221], v[84:87]
	v_mfma_f32_16x16x32_bf16 v[80:83], v[194:197], v[218:221], v[80:83]
	v_mfma_f32_16x16x32_bf16 v[68:71], v[184:187], v[226:229], v[68:71]
	v_mfma_f32_16x16x32_bf16 v[64:67], v[194:197], v[226:229], v[64:67]
	v_mfma_f32_16x16x32_bf16 v[116:119], v[188:191], v[206:209], v[116:119]
	v_mfma_f32_16x16x32_bf16 v[112:115], v[198:201], v[206:209], v[112:115]
	v_mfma_f32_16x16x32_bf16 v[100:103], v[188:191], v[214:217], v[100:103]
	v_mfma_f32_16x16x32_bf16 v[96:99], v[198:201], v[214:217], v[96:99]
	v_mfma_f32_16x16x32_bf16 v[84:87], v[188:191], v[222:225], v[84:87]
	v_mfma_f32_16x16x32_bf16 v[80:83], v[198:201], v[222:225], v[80:83]
	v_mfma_f32_16x16x32_bf16 v[68:71], v[188:191], v[230:233], v[68:71]
	v_mfma_f32_16x16x32_bf16 v[64:67], v[198:201], v[230:233], v[64:67]
	s_setprio 0
	s_barrier
; #define PG8_STAGE(bufoff, gbase, voff) do { _Pragma("unroll") for (int _i = 0; _i < 2; ++_i) \
;         __builtin_amdgcn_global_load_lds((const unsigned*)((const char*)(gbase) + (voff)[_i]), (LAS unsigned*)(lds + (bufoff) + ldsw + _i * 8192), 16, 0, PG8_AUX); } while (0)
; #define PG8_LDA(dst, b, h) do { _Pragma("unroll") for (int m = 0; m < 4; ++m) _Pragma("unroll") for (int k = 0; k < 2; ++k) dst[m][k] = *(const LAS bf16x8*)(lds + PG8_SA(b, h) + aoff + m * 2048 + k * 1024); } while (0)
; #define PG8_MMA(ai, bj, At, Bt) do { __builtin_amdgcn_s_setprio(1); _Pragma("unroll") for (int m = 0; m < 4; ++m) _Pragma("unroll") for (int n = 0; n < 2; ++n) _Pragma("unroll") for (int k = 0; k < 2; ++k) \
;         acc[ai][bj][m][n] = __builtin_amdgcn_mfma_f32_16x16x32_bf16(Bt[n][k], At[m][k], acc[ai][bj][m][n], 0, 0, 0); __builtin_amdgcn_s_setprio(0); } while (0)
; #define PG8_WAIT_V(n) asm volatile("s_waitcnt vmcnt(" #n ")" ::: "memory")
; #define PG8_WAIT_L(n) asm volatile("s_waitcnt lgkmcnt(" #n ")" ::: "memory")
; #define PG8_BAR __builtin_amdgcn_s_barrier()
; #define PG8_SCHED __builtin_amdgcn_sched_barrier(0)
; template <class Epi, class Sched>
; __device__ __forceinline__ void gemm_phase(LAS unsigned char* lds, const Gemm g, const Sched& S, const Epi& E) {
;     ...
;         for (int t = 0; t < nt; t += 2) {
;     ...
;             PG8_LDA(At, 1, 1); PG8_STAGE(PG8_SB(1, 0), b3, voffB); PG8_STAGE(PG8_SB(1, 1), b3 + hstepB, voffB); PG8_STAGE(PG8_SA(1, 0), a3, voffA);
;             PG8_WAIT_V(8); PG8_WAIT_L(0); PG8_BAR; PG8_MMA(1, 0, At, B0); PG8_MMA(1, 1, At, B1); PG8_BAR; PG8_SCHED;
	s_add_i32 s4, s4, s28
	v_lshl_add_u64 v[234:235], v[234:235], 0, s[12:13]
	s_mov_b32 m0, s4
	ds_read_b128 v[202:205], v182 offset:49152
	ds_read_b128 v[206:209], v182 offset:50176
	ds_read_b128 v[210:213], v182 offset:51200
	ds_read_b128 v[214:217], v182 offset:52224
	ds_read_b128 v[218:221], v182 offset:53248
	ds_read_b128 v[222:225], v182 offset:54272
	ds_read_b128 v[226:229], v182 offset:55296
	ds_read_b128 v[230:233], v182 offset:56320
	global_load_lds_dwordx4 v[234:235], off
	s_add_i32 m0, s4, 0x2000
	s_add_u32 s40, s40, 0x80080
	v_lshl_add_u64 v[234:235], v[236:237], 0, s[12:13]
	s_addc_u32 s41, s41, 0
	s_add_i32 s4, s65, s28
	global_load_lds_dwordx4 v[234:235], off
	v_lshl_add_u64 v[234:235], s[40:41], 0, v[136:137]
	s_mov_b32 m0, s4
	s_nop 0
	global_load_lds_dwordx4 v[234:235], off
	v_lshl_add_u64 v[234:235], s[40:41], 0, v[154:155]
	s_add_i32 m0, s4, 0x2000
	s_nop 0
	global_load_lds_dwordx4 v[234:235], off
	v_lshl_add_u64 v[234:235], v[238:239], 0, s[12:13]
	s_mov_b32 m0, s55
	s_nop 0
	global_load_lds_dwordx4 v[234:235], off
	v_lshl_add_u64 v[234:235], v[240:241], 0, s[12:13]
	s_mov_b32 m0, s56
	s_nop 0
	global_load_lds_dwordx4 v[234:235], off
	s_waitcnt vmcnt(8)
	s_waitcnt lgkmcnt(0)
	s_barrier
	s_setprio 1
	s_waitcnt lgkmcnt(0)
	v_mfma_f32_16x16x32_bf16 v[60:63], v[128:131], v[202:205], v[60:63]
	v_mfma_f32_16x16x32_bf16 v[56:59], v[164:167], v[202:205], v[56:59]
	v_mfma_f32_16x16x32_bf16 v[44:47], v[128:131], v[210:213], v[44:47]
	v_mfma_f32_16x16x32_bf16 v[40:43], v[164:167], v[210:213], v[40:43]
	v_mfma_f32_16x16x32_bf16 v[28:31], v[128:131], v[218:221], v[28:31]
	v_mfma_f32_16x16x32_bf16 v[24:27], v[164:167], v[218:221], v[24:27]
	v_mfma_f32_16x16x32_bf16 v[12:15], v[128:131], v[226:229], v[12:15]
	v_mfma_f32_16x16x32_bf16 v[8:11], v[164:167], v[226:229], v[8:11]
	v_mfma_f32_16x16x32_bf16 v[60:63], v[132:135], v[206:209], v[60:63]
	v_mfma_f32_16x16x32_bf16 v[56:59], v[168:171], v[206:209], v[56:59]
	v_mfma_f32_16x16x32_bf16 v[44:47], v[132:135], v[214:217], v[44:47]
	v_mfma_f32_16x16x32_bf16 v[40:43], v[168:171], v[214:217], v[40:43]
	v_mfma_f32_16x16x32_bf16 v[28:31], v[132:135], v[222:225], v[28:31]
	v_mfma_f32_16x16x32_bf16 v[24:27], v[168:171], v[222:225], v[24:27]
	v_mfma_f32_16x16x32_bf16 v[12:15], v[132:135], v[230:233], v[12:15]
	v_mfma_f32_16x16x32_bf16 v[8:11], v[168:171], v[230:233], v[8:11]
	v_mfma_f32_16x16x32_bf16 v[52:55], v[184:187], v[202:205], v[52:55]
	v_mfma_f32_16x16x32_bf16 v[48:51], v[194:197], v[202:205], v[48:51]
	v_mfma_f32_16x16x32_bf16 v[36:39], v[184:187], v[210:213], v[36:39]
	v_mfma_f32_16x16x32_bf16 v[32:35], v[194:197], v[210:213], v[32:35]
	v_mfma_f32_16x16x32_bf16 v[20:23], v[184:187], v[218:221], v[20:23]
	v_mfma_f32_16x16x32_bf16 v[16:19], v[194:197], v[218:221], v[16:19]
	v_mfma_f32_16x16x32_bf16 v[4:7], v[184:187], v[226:229], v[4:7]
	v_mfma_f32_16x16x32_bf16 v[0:3], v[194:197], v[226:229], v[0:3]
	v_mfma_f32_16x16x32_bf16 v[52:55], v[188:191], v[206:209], v[52:55]
	v_mfma_f32_16x16x32_bf16 v[48:51], v[198:201], v[206:209], v[48:51]
	v_mfma_f32_16x16x32_bf16 v[36:39], v[188:191], v[214:217], v[36:39]
	v_mfma_f32_16x16x32_bf16 v[32:35], v[198:201], v[214:217], v[32:35]
	v_mfma_f32_16x16x32_bf16 v[20:23], v[188:191], v[222:225], v[20:23]
	v_mfma_f32_16x16x32_bf16 v[16:19], v[198:201], v[222:225], v[16:19]
	v_mfma_f32_16x16x32_bf16 v[4:7], v[188:191], v[230:233], v[4:7]
	v_mfma_f32_16x16x32_bf16 v[0:3], v[198:201], v[230:233], v[0:3]
	s_setprio 0
	s_barrier
	s_add_u32 s22, s22, 0x100
	s_addc_u32 s23, s23, 0
	s_add_u32 s27, s27, 0x100
	s_addc_u32 s47, s47, 0
	s_cmp_ge_u32 s49, s61
	s_mov_b32 s4, s49
	s_cbranch_scc0 .LBB0_141
	s_and_b64 vcc, exec, s[44:45]
	s_cbranch_vccz .LBB0_144
	s_barrier

; #define PG8_STAGE(bufoff, gbase, voff) do { _Pragma("unroll") for (int _i = 0; _i < 2; ++_i) \
;         __builtin_amdgcn_global_load_lds((const unsigned*)((const char*)(gbase) + (voff)[_i]), (LAS unsigned*)(lds + (bufoff) + ldsw + _i * 8192), 16, 0, PG8_AUX); } while (0)
; #define PG8_LDA(dst, b, h) do { _Pragma("unroll") for (int m = 0; m < 4; ++m) _Pragma("unroll") for (int k = 0; k < 2; ++k) dst[m][k] = *(const LAS bf16x8*)(lds + PG8_SA(b, h) + aoff + m * 2048 + k * 1024); } while (0)
; #define PG8_LDB(dst, b, h) do { _Pragma("unroll") for (int n = 0; n < 2; ++n) _Pragma("unroll") for (int k = 0; k < 2; ++k) dst[n][k] = *(const LAS bf16x8*)(lds + PG8_SB(b, h) + boff + n * 2048 + k * 1024); } while (0)
; #define PG8_MMA(ai, bj, At, Bt) do { __builtin_amdgcn_s_setprio(1); _Pragma("unroll") for (int m = 0; m < 4; ++m) _Pragma("unroll") for (int n = 0; n < 2; ++n) _Pragma("unroll") for (int k = 0; k < 2; ++k) \
;         acc[ai][bj][m][n] = __builtin_amdgcn_mfma_f32_16x16x32_bf16(Bt[n][k], At[m][k], acc[ai][bj][m][n], 0, 0, 0); __builtin_amdgcn_s_setprio(0); } while (0)
; #define PG8_WAIT_V(n) asm volatile("s_waitcnt vmcnt(" #n ")" ::: "memory")
; #define PG8_WAIT_L(n) asm volatile("s_waitcnt lgkmcnt(" #n ")" ::: "memory")
; #define PG8_BAR __builtin_amdgcn_s_barrier()
; #define PG8_SCHED __builtin_amdgcn_sched_barrier(0)
; template <class Epi, class Sched>
; __device__ __forceinline__ void gemm_phase(LAS unsigned char* lds, const Gemm g, const Sched& S, const Epi& E) {
;     ...
;         for (int t = 0; t < nt; t += 2) {
;             const bool last = (t == nt - 2);
;             const char* a1 = cA + (size_t)(t + 1) * kstep;
;             const char* a2 = last ? nA : cA + (size_t)(t + 2) * kstep; const char* b2 = last ? nB : cB + (size_t)(t + 2) * kstep;
;             const char* a3 = a2 + kstep; const char* b3 = b2 + kstep;
;     ...
;             PG8_LDB(B0, 0, 0); PG8_LDB(B1, 0, 1); PG8_SCHED; PG8_LDA(At, 0, 0); PG8_STAGE(PG8_SA(1, 1), a1 + hstepA, voffA);
;             PG8_WAIT_V(8); PG8_WAIT_L(0); PG8_BAR; PG8_MMA(0, 0, At, B0); PG8_MMA(0, 1, At, B1); PG8_BAR; PG8_SCHED;
;             PG8_LDA(At, 0, 1); PG8_STAGE(PG8_SB(0, 0), b2, voffB); PG8_STAGE(PG8_SB(0, 1), b2 + hstepB, voffB); PG8_STAGE(PG8_SA(0, 0), a2, voffA);
;             PG8_WAIT_V(8); PG8_WAIT_L(0); PG8_BAR; PG8_MMA(1, 0, At, B0); PG8_MMA(1, 1, At, B1); PG8_BAR; PG8_SCHED;
.LBB0_197:
	s_add_u32 s4, s48, 0xfffe0080
	s_addc_u32 s50, s49, -1
	s_add_i32 s64, 0, 0x10000
	s_cmp_eq_u32 s63, 4
	s_cselect_b32 s53, s27, s50
	s_cselect_b32 s52, s41, s4
	v_add_u32_e32 v172, s64, v161
	s_cselect_b32 s51, s43, s62
	s_cselect_b32 s50, s60, s61
	s_add_i32 s4, 0, 0x14000
	ds_read_b128 v[156:159], v172
	ds_read_b128 v[164:167], v172 offset:1024
	ds_read_b128 v[168:171], v172 offset:2048
	ds_read_b128 v[182:185], v172 offset:3072
	v_add_u32_e32 v172, s4, v161
	ds_read_b128 v[186:189], v172
	ds_read_b128 v[194:197], v172 offset:1024
	ds_read_b128 v[198:201], v172 offset:2048
	ds_read_b128 v[202:205], v172 offset:3072
	v_lshl_add_u64 v[172:173], s[48:49], 0, v[134:135]
	s_add_i32 m0, s30, 0xc000
	ds_read_b128 v[206:209], v163
	ds_read_b128 v[210:213], v163 offset:1024
	ds_read_b128 v[214:217], v163 offset:2048
	ds_read_b128 v[218:221], v163 offset:3072
	ds_read_b128 v[222:225], v163 offset:4096
	ds_read_b128 v[226:229], v163 offset:5120
	ds_read_b128 v[230:233], v163 offset:6144
	ds_read_b128 v[234:237], v163 offset:7168
	global_load_lds_dwordx4 v[172:173], off
	v_lshl_add_u64 v[172:173], s[48:49], 0, v[154:155]
	s_add_i32 m0, s30, 0xe000
	s_nop 0
	global_load_lds_dwordx4 v[172:173], off
	s_waitcnt vmcnt(8)
	s_waitcnt lgkmcnt(0)
	s_barrier
	s_setprio 1
	s_waitcnt lgkmcnt(0)
	v_mfma_f32_16x16x32_bf16 v[124:127], v[156:159], v[206:209], v[124:127]
	v_mfma_f32_16x16x32_bf16 v[120:123], v[168:171], v[206:209], v[120:123]
	v_mfma_f32_16x16x32_bf16 v[108:111], v[156:159], v[214:217], v[108:111]
	v_mfma_f32_16x16x32_bf16 v[104:107], v[168:171], v[214:217], v[104:107]
	v_mfma_f32_16x16x32_bf16 v[96:99], v[156:159], v[222:225], v[96:99]
	v_mfma_f32_16x16x32_bf16 v[88:91], v[168:171], v[222:225], v[88:91]
	v_mfma_f32_16x16x32_bf16 v[76:79], v[156:159], v[230:233], v[76:79]
	v_mfma_f32_16x16x32_bf16 v[72:75], v[168:171], v[230:233], v[72:75]
	v_mfma_f32_16x16x32_bf16 v[124:127], v[164:167], v[210:213], v[124:127]
	v_mfma_f32_16x16x32_bf16 v[120:123], v[182:185], v[210:213], v[120:123]
	v_mfma_f32_16x16x32_bf16 v[108:111], v[164:167], v[218:221], v[108:111]
	v_mfma_f32_16x16x32_bf16 v[104:107], v[182:185], v[218:221], v[104:107]
	v_mfma_f32_16x16x32_bf16 v[96:99], v[164:167], v[226:229], v[96:99]
	v_mfma_f32_16x16x32_bf16 v[88:91], v[182:185], v[226:229], v[88:91]
	v_mfma_f32_16x16x32_bf16 v[76:79], v[164:167], v[234:237], v[76:79]
	v_mfma_f32_16x16x32_bf16 v[72:75], v[182:185], v[234:237], v[72:75]
	v_mfma_f32_16x16x32_bf16 v[116:119], v[186:189], v[206:209], v[116:119]
	v_mfma_f32_16x16x32_bf16 v[112:115], v[198:201], v[206:209], v[112:115]
	v_mfma_f32_16x16x32_bf16 v[100:103], v[186:189], v[214:217], v[100:103]
	v_mfma_f32_16x16x32_bf16 v[92:95], v[198:201], v[214:217], v[92:95]
	v_mfma_f32_16x16x32_bf16 v[84:87], v[186:189], v[222:225], v[84:87]
	v_mfma_f32_16x16x32_bf16 v[80:83], v[198:201], v[222:225], v[80:83]
	v_mfma_f32_16x16x32_bf16 v[68:71], v[186:189], v[230:233], v[68:71]
	v_mfma_f32_16x16x32_bf16 v[64:67], v[198:201], v[230:233], v[64:67]
	v_mfma_f32_16x16x32_bf16 v[116:119], v[194:197], v[210:213], v[116:119]
	v_mfma_f32_16x16x32_bf16 v[112:115], v[202:205], v[210:213], v[112:115]
	v_mfma_f32_16x16x32_bf16 v[100:103], v[194:197], v[218:221], v[100:103]
	v_mfma_f32_16x16x32_bf16 v[92:95], v[202:205], v[218:221], v[92:95]
	v_mfma_f32_16x16x32_bf16 v[84:87], v[194:197], v[226:229], v[84:87]
	v_mfma_f32_16x16x32_bf16 v[80:83], v[202:205], v[226:229], v[80:83]
	v_mfma_f32_16x16x32_bf16 v[68:71], v[194:197], v[234:237], v[68:71]
	v_mfma_f32_16x16x32_bf16 v[64:67], v[202:205], v[234:237], v[64:67]
	s_setprio 0
	s_barrier
	s_add_i32 s64, s64, s28
	v_lshl_add_u64 v[172:173], s[50:51], 0, v[136:137]
	s_mov_b32 m0, s64
	ds_read_b128 v[206:209], v163 offset:16384
	ds_read_b128 v[210:213], v163 offset:17408
	ds_read_b128 v[214:217], v163 offset:18432
	ds_read_b128 v[218:221], v163 offset:19456
	ds_read_b128 v[222:225], v163 offset:20480
	ds_read_b128 v[226:229], v163 offset:21504
	ds_read_b128 v[230:233], v163 offset:22528
	ds_read_b128 v[234:237], v163 offset:23552
	global_load_lds_dwordx4 v[172:173], off
	s_add_i32 m0, s64, 0x2000
	s_add_u32 s64, s50, 0x20000
	v_lshl_add_u64 v[190:191], s[50:51], 0, v[128:129]
	s_addc_u32 s65, s51, 0
	s_add_i32 s4, s4, s28
	global_load_lds_dwordx4 v[190:191], off
	v_lshl_add_u64 v[238:239], s[64:65], 0, v[136:137]
	s_mov_b32 m0, s4
	v_lshl_add_u64 v[240:241], s[52:53], 0, v[130:131]
	global_load_lds_dwordx4 v[238:239], off
	v_lshl_add_u64 v[238:239], s[64:65], 0, v[128:129]
	s_add_i32 m0, s4, 0x2000
	s_nop 0
	global_load_lds_dwordx4 v[238:239], off
	v_lshl_add_u64 v[238:239], s[52:53], 0, v[132:133]
	s_mov_b32 m0, s30
	s_nop 0
	global_load_lds_dwordx4 v[238:239], off
	s_mov_b32 m0, s34
	s_nop 0
	global_load_lds_dwordx4 v[240:241], off
	s_waitcnt vmcnt(8)
	s_waitcnt lgkmcnt(0)
	s_barrier
; #define PG8_STAGE(bufoff, gbase, voff) do { _Pragma("unroll") for (int _i = 0; _i < 2; ++_i) \
;         __builtin_amdgcn_global_load_lds((const unsigned*)((const char*)(gbase) + (voff)[_i]), (LAS unsigned*)(lds + (bufoff) + ldsw + _i * 8192), 16, 0, PG8_AUX); } while (0)
; #define PG8_LDA(dst, b, h) do { _Pragma("unroll") for (int m = 0; m < 4; ++m) _Pragma("unroll") for (int k = 0; k < 2; ++k) dst[m][k] = *(const LAS bf16x8*)(lds + PG8_SA(b, h) + aoff + m * 2048 + k * 1024); } while (0)
; #define PG8_LDB(dst, b, h) do { _Pragma("unroll") for (int n = 0; n < 2; ++n) _Pragma("unroll") for (int k = 0; k < 2; ++k) dst[n][k] = *(const LAS bf16x8*)(lds + PG8_SB(b, h) + boff + n * 2048 + k * 1024); } while (0)
; #define PG8_MMA(ai, bj, At, Bt) do { __builtin_amdgcn_s_setprio(1); _Pragma("unroll") for (int m = 0; m < 4; ++m) _Pragma("unroll") for (int n = 0; n < 2; ++n) _Pragma("unroll") for (int k = 0; k < 2; ++k) \
;         acc[ai][bj][m][n] = __builtin_amdgcn_mfma_f32_16x16x32_bf16(Bt[n][k], At[m][k], acc[ai][bj][m][n], 0, 0, 0); __builtin_amdgcn_s_setprio(0); } while (0)
; #define PG8_WAIT_V(n) asm volatile("s_waitcnt vmcnt(" #n ")" ::: "memory")
; #define PG8_WAIT_L(n) asm volatile("s_waitcnt lgkmcnt(" #n ")" ::: "memory")
; #define PG8_BAR __builtin_amdgcn_s_barrier()
; #define PG8_SCHED __builtin_amdgcn_sched_barrier(0)
; template <class Epi, class Sched>
; __device__ __forceinline__ void gemm_phase(LAS unsigned char* lds, const Gemm g, const Sched& S, const Epi& E) {
;     ...
;             PG8_WAIT_V(8); PG8_WAIT_L(0); PG8_BAR; PG8_MMA(1, 0, At, B0); PG8_MMA(1, 1, At, B1); PG8_BAR; PG8_SCHED;
;             PG8_LDB(B0, 1, 0); PG8_LDB(B1, 1, 1); PG8_SCHED; PG8_LDA(At, 1, 0); PG8_STAGE(PG8_SA(0, 1), a2 + hstepA, voffA);
;             PG8_WAIT_V(8); PG8_WAIT_L(0); PG8_BAR; PG8_MMA(0, 0, At, B0); PG8_MMA(0, 1, At, B1); PG8_BAR; PG8_SCHED;
	s_setprio 1
	s_waitcnt lgkmcnt(0)
	v_mfma_f32_16x16x32_bf16 v[60:63], v[156:159], v[206:209], v[60:63]
	v_mfma_f32_16x16x32_bf16 v[56:59], v[168:171], v[206:209], v[56:59]
	v_mfma_f32_16x16x32_bf16 v[44:47], v[156:159], v[214:217], v[44:47]
	v_mfma_f32_16x16x32_bf16 v[40:43], v[168:171], v[214:217], v[40:43]
	v_mfma_f32_16x16x32_bf16 v[28:31], v[156:159], v[222:225], v[28:31]
	v_mfma_f32_16x16x32_bf16 v[24:27], v[168:171], v[222:225], v[24:27]
	v_mfma_f32_16x16x32_bf16 v[12:15], v[156:159], v[230:233], v[12:15]
	v_mfma_f32_16x16x32_bf16 v[8:11], v[168:171], v[230:233], v[8:11]
	v_mfma_f32_16x16x32_bf16 v[60:63], v[164:167], v[210:213], v[60:63]
	v_mfma_f32_16x16x32_bf16 v[56:59], v[182:185], v[210:213], v[56:59]
	v_mfma_f32_16x16x32_bf16 v[44:47], v[164:167], v[218:221], v[44:47]
	v_mfma_f32_16x16x32_bf16 v[40:43], v[182:185], v[218:221], v[40:43]
	v_mfma_f32_16x16x32_bf16 v[28:31], v[164:167], v[226:229], v[28:31]
	v_mfma_f32_16x16x32_bf16 v[24:27], v[182:185], v[226:229], v[24:27]
	v_mfma_f32_16x16x32_bf16 v[12:15], v[164:167], v[234:237], v[12:15]
	v_mfma_f32_16x16x32_bf16 v[8:11], v[182:185], v[234:237], v[8:11]
	v_mfma_f32_16x16x32_bf16 v[52:55], v[186:189], v[206:209], v[52:55]
	v_mfma_f32_16x16x32_bf16 v[48:51], v[198:201], v[206:209], v[48:51]
	v_mfma_f32_16x16x32_bf16 v[36:39], v[186:189], v[214:217], v[36:39]
	v_mfma_f32_16x16x32_bf16 v[32:35], v[198:201], v[214:217], v[32:35]
	v_mfma_f32_16x16x32_bf16 v[20:23], v[186:189], v[222:225], v[20:23]
	v_mfma_f32_16x16x32_bf16 v[16:19], v[198:201], v[222:225], v[16:19]
	v_mfma_f32_16x16x32_bf16 v[4:7], v[186:189], v[230:233], v[4:7]
	v_mfma_f32_16x16x32_bf16 v[0:3], v[198:201], v[230:233], v[0:3]
	v_mfma_f32_16x16x32_bf16 v[52:55], v[194:197], v[210:213], v[52:55]
	v_mfma_f32_16x16x32_bf16 v[48:51], v[202:205], v[210:213], v[48:51]
	v_mfma_f32_16x16x32_bf16 v[36:39], v[194:197], v[218:221], v[36:39]
	v_mfma_f32_16x16x32_bf16 v[32:35], v[202:205], v[218:221], v[32:35]
	v_mfma_f32_16x16x32_bf16 v[20:23], v[194:197], v[226:229], v[20:23]
	v_mfma_f32_16x16x32_bf16 v[16:19], v[202:205], v[226:229], v[16:19]
	v_mfma_f32_16x16x32_bf16 v[4:7], v[194:197], v[234:237], v[4:7]
	v_mfma_f32_16x16x32_bf16 v[0:3], v[202:205], v[234:237], v[0:3]
	s_setprio 0
	s_barrier
	s_add_i32 s4, 0, 0x18000
	v_add_u32_e32 v181, s4, v161
	s_add_i32 s64, 0, 0x1c000
	ds_read_b128 v[156:159], v181
	ds_read_b128 v[164:167], v181 offset:1024
	ds_read_b128 v[168:171], v181 offset:2048
	ds_read_b128 v[182:185], v181 offset:3072
	v_add_u32_e32 v181, s64, v161
	ds_read_b128 v[186:189], v181
	ds_read_b128 v[194:197], v181 offset:1024
	ds_read_b128 v[198:201], v181 offset:2048
	ds_read_b128 v[202:205], v181 offset:3072
	s_add_u32 s52, s52, 0x20000
	s_addc_u32 s53, s53, 0
	s_mov_b32 m0, s36
	v_lshl_add_u64 v[242:243], s[52:53], 0, v[132:133]
	ds_read_b128 v[206:209], v163 offset:32768
	ds_read_b128 v[210:213], v163 offset:33792
	ds_read_b128 v[214:217], v163 offset:34816
	ds_read_b128 v[218:221], v163 offset:35840
	ds_read_b128 v[222:225], v163 offset:36864
	ds_read_b128 v[226:229], v163 offset:37888
	ds_read_b128 v[230:233], v163 offset:38912
	ds_read_b128 v[234:237], v163 offset:39936
	global_load_lds_dwordx4 v[242:243], off
	v_lshl_add_u64 v[242:243], s[52:53], 0, v[130:131]
	s_mov_b32 m0, s54
	s_nop 0
	global_load_lds_dwordx4 v[242:243], off
	s_waitcnt vmcnt(8)
	s_waitcnt lgkmcnt(0)
	s_barrier
	s_setprio 1
	s_waitcnt lgkmcnt(0)
	v_mfma_f32_16x16x32_bf16 v[124:127], v[156:159], v[206:209], v[124:127]
	v_mfma_f32_16x16x32_bf16 v[120:123], v[168:171], v[206:209], v[120:123]
	v_mfma_f32_16x16x32_bf16 v[108:111], v[156:159], v[214:217], v[108:111]
	v_mfma_f32_16x16x32_bf16 v[104:107], v[168:171], v[214:217], v[104:107]
	v_mfma_f32_16x16x32_bf16 v[96:99], v[156:159], v[222:225], v[96:99]
	v_mfma_f32_16x16x32_bf16 v[88:91], v[168:171], v[222:225], v[88:91]
	v_mfma_f32_16x16x32_bf16 v[76:79], v[156:159], v[230:233], v[76:79]
	v_mfma_f32_16x16x32_bf16 v[72:75], v[168:171], v[230:233], v[72:75]
	v_mfma_f32_16x16x32_bf16 v[124:127], v[164:167], v[210:213], v[124:127]
	v_mfma_f32_16x16x32_bf16 v[120:123], v[182:185], v[210:213], v[120:123]
	v_mfma_f32_16x16x32_bf16 v[108:111], v[164:167], v[218:221], v[108:111]
	v_mfma_f32_16x16x32_bf16 v[104:107], v[182:185], v[218:221], v[104:107]
	v_mfma_f32_16x16x32_bf16 v[96:99], v[164:167], v[226:229], v[96:99]
	v_mfma_f32_16x16x32_bf16 v[88:91], v[182:185], v[226:229], v[88:91]
	v_mfma_f32_16x16x32_bf16 v[76:79], v[164:167], v[234:237], v[76:79]
	v_mfma_f32_16x16x32_bf16 v[72:75], v[182:185], v[234:237], v[72:75]
	v_mfma_f32_16x16x32_bf16 v[116:119], v[186:189], v[206:209], v[116:119]
	v_mfma_f32_16x16x32_bf16 v[112:115], v[198:201], v[206:209], v[112:115]
	v_mfma_f32_16x16x32_bf16 v[100:103], v[186:189], v[214:217], v[100:103]
	v_mfma_f32_16x16x32_bf16 v[92:95], v[198:201], v[214:217], v[92:95]
	v_mfma_f32_16x16x32_bf16 v[84:87], v[186:189], v[222:225], v[84:87]
	v_mfma_f32_16x16x32_bf16 v[80:83], v[198:201], v[222:225], v[80:83]
	v_mfma_f32_16x16x32_bf16 v[68:71], v[186:189], v[230:233], v[68:71]
	v_mfma_f32_16x16x32_bf16 v[64:67], v[198:201], v[230:233], v[64:67]
	v_mfma_f32_16x16x32_bf16 v[116:119], v[194:197], v[210:213], v[116:119]
	v_mfma_f32_16x16x32_bf16 v[112:115], v[202:205], v[210:213], v[112:115]
	v_mfma_f32_16x16x32_bf16 v[100:103], v[194:197], v[218:221], v[100:103]
	v_mfma_f32_16x16x32_bf16 v[92:95], v[202:205], v[218:221], v[92:95]
	v_mfma_f32_16x16x32_bf16 v[84:87], v[194:197], v[226:229], v[84:87]
	v_mfma_f32_16x16x32_bf16 v[80:83], v[202:205], v[226:229], v[80:83]
	v_mfma_f32_16x16x32_bf16 v[68:71], v[194:197], v[234:237], v[68:71]
	v_mfma_f32_16x16x32_bf16 v[64:67], v[202:205], v[234:237], v[64:67]
	s_setprio 0
	s_barrier
; #define PG8_STAGE(bufoff, gbase, voff) do { _Pragma("unroll") for (int _i = 0; _i < 2; ++_i) \
;         __builtin_amdgcn_global_load_lds((const unsigned*)((const char*)(gbase) + (voff)[_i]), (LAS unsigned*)(lds + (bufoff) + ldsw + _i * 8192), 16, 0, PG8_AUX); } while (0)
; #define PG8_LDA(dst, b, h) do { _Pragma("unroll") for (int m = 0; m < 4; ++m) _Pragma("unroll") for (int k = 0; k < 2; ++k) dst[m][k] = *(const LAS bf16x8*)(lds + PG8_SA(b, h) + aoff + m * 2048 + k * 1024); } while (0)
; #define PG8_MMA(ai, bj, At, Bt) do { __builtin_amdgcn_s_setprio(1); _Pragma("unroll") for (int m = 0; m < 4; ++m) _Pragma("unroll") for (int n = 0; n < 2; ++n) _Pragma("unroll") for (int k = 0; k < 2; ++k) \
;         acc[ai][bj][m][n] = __builtin_amdgcn_mfma_f32_16x16x32_bf16(Bt[n][k], At[m][k], acc[ai][bj][m][n], 0, 0, 0); __builtin_amdgcn_s_setprio(0); } while (0)
; #define PG8_WAIT_V(n) asm volatile("s_waitcnt vmcnt(" #n ")" ::: "memory")
; #define PG8_WAIT_L(n) asm volatile("s_waitcnt lgkmcnt(" #n ")" ::: "memory")
; #define PG8_BAR __builtin_amdgcn_s_barrier()
; #define PG8_SCHED __builtin_amdgcn_sched_barrier(0)
; template <class Epi, class Sched>
; __device__ __forceinline__ void gemm_phase(LAS unsigned char* lds, const Gemm g, const Sched& S, const Epi& E) {
;     ...
;         for (int t = 0; t < nt; t += 2) {
;     ...
;             PG8_LDA(At, 1, 1); PG8_STAGE(PG8_SB(1, 0), b3, voffB); PG8_STAGE(PG8_SB(1, 1), b3 + hstepB, voffB); PG8_STAGE(PG8_SA(1, 0), a3, voffA);
;             PG8_WAIT_V(8); PG8_WAIT_L(0); PG8_BAR; PG8_MMA(1, 0, At, B0); PG8_MMA(1, 1, At, B1); PG8_BAR; PG8_SCHED;
	s_add_i32 s4, s4, s28
	v_lshl_add_u64 v[172:173], v[172:173], 0, s[12:13]
	s_mov_b32 m0, s4
	ds_read_b128 v[206:209], v163 offset:49152
	ds_read_b128 v[210:213], v163 offset:50176
	ds_read_b128 v[214:217], v163 offset:51200
	ds_read_b128 v[218:221], v163 offset:52224
	ds_read_b128 v[222:225], v163 offset:53248
	ds_read_b128 v[226:229], v163 offset:54272
	ds_read_b128 v[230:233], v163 offset:55296
	ds_read_b128 v[234:237], v163 offset:56320
	global_load_lds_dwordx4 v[172:173], off
	s_add_i32 m0, s4, 0x2000
	s_add_u32 s50, s50, 0x20080
	v_lshl_add_u64 v[172:173], v[190:191], 0, s[12:13]
	s_addc_u32 s51, s51, 0
	s_add_i32 s4, s64, s28
	global_load_lds_dwordx4 v[172:173], off
	v_lshl_add_u64 v[172:173], s[50:51], 0, v[136:137]
	s_mov_b32 m0, s4
	s_nop 0
	global_load_lds_dwordx4 v[172:173], off
	v_lshl_add_u64 v[172:173], s[50:51], 0, v[128:129]
	s_add_i32 m0, s4, 0x2000
	s_nop 0
	global_load_lds_dwordx4 v[172:173], off
	v_lshl_add_u64 v[172:173], v[238:239], 0, s[12:13]
	s_mov_b32 m0, s55
	s_nop 0
	global_load_lds_dwordx4 v[172:173], off
	v_lshl_add_u64 v[172:173], v[240:241], 0, s[12:13]
	s_mov_b32 m0, s56
	s_nop 0
	global_load_lds_dwordx4 v[172:173], off
	s_waitcnt vmcnt(8)
	s_waitcnt lgkmcnt(0)
	s_barrier
	s_setprio 1
	s_waitcnt lgkmcnt(0)
	v_mfma_f32_16x16x32_bf16 v[60:63], v[156:159], v[206:209], v[60:63]
	v_mfma_f32_16x16x32_bf16 v[56:59], v[168:171], v[206:209], v[56:59]
	v_mfma_f32_16x16x32_bf16 v[44:47], v[156:159], v[214:217], v[44:47]
	v_mfma_f32_16x16x32_bf16 v[40:43], v[168:171], v[214:217], v[40:43]
	v_mfma_f32_16x16x32_bf16 v[28:31], v[156:159], v[222:225], v[28:31]
	v_mfma_f32_16x16x32_bf16 v[24:27], v[168:171], v[222:225], v[24:27]
	v_mfma_f32_16x16x32_bf16 v[12:15], v[156:159], v[230:233], v[12:15]
	v_mfma_f32_16x16x32_bf16 v[8:11], v[168:171], v[230:233], v[8:11]
	v_mfma_f32_16x16x32_bf16 v[60:63], v[164:167], v[210:213], v[60:63]
	v_mfma_f32_16x16x32_bf16 v[56:59], v[182:185], v[210:213], v[56:59]
	v_mfma_f32_16x16x32_bf16 v[44:47], v[164:167], v[218:221], v[44:47]
	v_mfma_f32_16x16x32_bf16 v[40:43], v[182:185], v[218:221], v[40:43]
	v_mfma_f32_16x16x32_bf16 v[28:31], v[164:167], v[226:229], v[28:31]
	v_mfma_f32_16x16x32_bf16 v[24:27], v[182:185], v[226:229], v[24:27]
	v_mfma_f32_16x16x32_bf16 v[12:15], v[164:167], v[234:237], v[12:15]
	v_mfma_f32_16x16x32_bf16 v[8:11], v[182:185], v[234:237], v[8:11]
	v_mfma_f32_16x16x32_bf16 v[52:55], v[186:189], v[206:209], v[52:55]
	v_mfma_f32_16x16x32_bf16 v[48:51], v[198:201], v[206:209], v[48:51]
	v_mfma_f32_16x16x32_bf16 v[36:39], v[186:189], v[214:217], v[36:39]
	v_mfma_f32_16x16x32_bf16 v[32:35], v[198:201], v[214:217], v[32:35]
	v_mfma_f32_16x16x32_bf16 v[20:23], v[186:189], v[222:225], v[20:23]
	v_mfma_f32_16x16x32_bf16 v[16:19], v[198:201], v[222:225], v[16:19]
	v_mfma_f32_16x16x32_bf16 v[4:7], v[186:189], v[230:233], v[4:7]
	v_mfma_f32_16x16x32_bf16 v[0:3], v[198:201], v[230:233], v[0:3]
	v_mfma_f32_16x16x32_bf16 v[52:55], v[194:197], v[210:213], v[52:55]
	v_mfma_f32_16x16x32_bf16 v[48:51], v[202:205], v[210:213], v[48:51]
	v_mfma_f32_16x16x32_bf16 v[36:39], v[194:197], v[218:221], v[36:39]
	v_mfma_f32_16x16x32_bf16 v[32:35], v[202:205], v[218:221], v[32:35]
	v_mfma_f32_16x16x32_bf16 v[20:23], v[194:197], v[226:229], v[20:23]
	v_mfma_f32_16x16x32_bf16 v[16:19], v[202:205], v[226:229], v[16:19]
	v_mfma_f32_16x16x32_bf16 v[4:7], v[194:197], v[234:237], v[4:7]
	v_mfma_f32_16x16x32_bf16 v[0:3], v[202:205], v[234:237], v[0:3]
	s_setprio 0
	s_barrier
	s_add_i32 s63, s63, 2
	s_add_u32 s48, s48, 0x100
	s_addc_u32 s49, s49, 0
	s_add_u32 s61, s61, 0x100
	s_addc_u32 s62, s62, 0
	s_cmp_gt_u32 s63, 5
	s_cbranch_scc0 .LBB0_197
	s_and_b64 vcc, exec, s[22:23]
	s_cbranch_vccz .LBB0_200
	s_barrier

; #define PG8_STAGE(bufoff, gbase, voff) do { _Pragma("unroll") for (int _i = 0; _i < 2; ++_i) \
;         __builtin_amdgcn_global_load_lds((const unsigned*)((const char*)(gbase) + (voff)[_i]), (LAS unsigned*)(lds + (bufoff) + ldsw + _i * 8192), 16, 0, PG8_AUX); } while (0)
; #define PG8_LDA(dst, b, h) do { _Pragma("unroll") for (int m = 0; m < 4; ++m) _Pragma("unroll") for (int k = 0; k < 2; ++k) dst[m][k] = *(const LAS bf16x8*)(lds + PG8_SA(b, h) + aoff + m * 2048 + k * 1024); } while (0)
; #define PG8_LDB(dst, b, h) do { _Pragma("unroll") for (int n = 0; n < 2; ++n) _Pragma("unroll") for (int k = 0; k < 2; ++k) dst[n][k] = *(const LAS bf16x8*)(lds + PG8_SB(b, h) + boff + n * 2048 + k * 1024); } while (0)
; #define PG8_MMA(ai, bj, At, Bt) do { __builtin_amdgcn_s_setprio(1); _Pragma("unroll") for (int m = 0; m < 4; ++m) _Pragma("unroll") for (int n = 0; n < 2; ++n) _Pragma("unroll") for (int k = 0; k < 2; ++k) \
;         acc[ai][bj][m][n] = __builtin_amdgcn_mfma_f32_16x16x32_bf16(Bt[n][k], At[m][k], acc[ai][bj][m][n], 0, 0, 0); __builtin_amdgcn_s_setprio(0); } while (0)
; #define PG8_WAIT_V(n) asm volatile("s_waitcnt vmcnt(" #n ")" ::: "memory")
; #define PG8_WAIT_L(n) asm volatile("s_waitcnt lgkmcnt(" #n ")" ::: "memory")
; #define PG8_BAR __builtin_amdgcn_s_barrier()
; #define PG8_SCHED __builtin_amdgcn_sched_barrier(0)
; template <class Epi, class Sched>
; __device__ __forceinline__ void gemm_phase(LAS unsigned char* lds, const Gemm g, const Sched& S, const Epi& E) {
;     ...
;         for (int t = 0; t < nt; t += 2) {
;             const bool last = (t == nt - 2);
;             const char* a1 = cA + (size_t)(t + 1) * kstep;
;             const char* a2 = last ? nA : cA + (size_t)(t + 2) * kstep; const char* b2 = last ? nB : cB + (size_t)(t + 2) * kstep;
;             const char* a3 = a2 + kstep; const char* b3 = b2 + kstep;
;     ...
;             PG8_LDB(B0, 0, 0); PG8_LDB(B1, 0, 1); PG8_SCHED; PG8_LDA(At, 0, 0); PG8_STAGE(PG8_SA(1, 1), a1 + hstepA, voffA);
;             PG8_WAIT_V(8); PG8_WAIT_L(0); PG8_BAR; PG8_MMA(0, 0, At, B0); PG8_MMA(0, 1, At, B1); PG8_BAR; PG8_SCHED;
;             PG8_LDA(At, 0, 1); PG8_STAGE(PG8_SB(0, 0), b2, voffB); PG8_STAGE(PG8_SB(0, 1), b2 + hstepB, voffB); PG8_STAGE(PG8_SA(0, 0), a2, voffA);
;             PG8_WAIT_V(8); PG8_WAIT_L(0); PG8_BAR; PG8_MMA(1, 0, At, B0); PG8_MMA(1, 1, At, B1); PG8_BAR; PG8_SCHED;
.LBB0_382:
	s_add_u32 s4, s0, 0xfff80080
	s_addc_u32 s22, s1, -1
	s_add_i32 s78, 0, 0x10000
	s_cmp_eq_u32 s65, 28
	s_cselect_b32 s41, s20, s22
	s_cselect_b32 s40, s27, s4
	v_add_u32_e32 v136, s78, v182
	s_cselect_b32 s23, s49, s64
	s_cselect_b32 s22, s51, s63
	s_add_i32 s4, 0, 0x14000
	ds_read_b128 v[160:163], v136
	ds_read_b128 v[164:167], v136 offset:1024
	ds_read_b128 v[168:171], v136 offset:2048
	ds_read_b128 v[186:189], v136 offset:3072
	v_add_u32_e32 v136, s4, v182
	ds_read_b128 v[194:197], v136
	ds_read_b128 v[198:201], v136 offset:1024
	ds_read_b128 v[202:205], v136 offset:2048
	ds_read_b128 v[206:209], v136 offset:3072
	v_lshl_add_u64 v[172:173], s[0:1], 0, v[156:157]
	s_add_i32 m0, s30, 0xc000
	ds_read_b128 v[210:213], v184
	ds_read_b128 v[214:217], v184 offset:1024
	ds_read_b128 v[218:221], v184 offset:2048
	ds_read_b128 v[222:225], v184 offset:3072
	ds_read_b128 v[226:229], v184 offset:4096
	ds_read_b128 v[230:233], v184 offset:5120
	ds_read_b128 v[234:237], v184 offset:6144
	ds_read_b128 v[238:241], v184 offset:7168
	global_load_lds_dwordx4 v[172:173], off
	v_lshl_add_u64 v[172:173], s[0:1], 0, v[158:159]
	s_add_i32 m0, s30, 0xe000
	s_nop 0
	global_load_lds_dwordx4 v[172:173], off
	s_waitcnt vmcnt(8)
	s_waitcnt lgkmcnt(0)
	s_barrier
	s_setprio 1
	s_waitcnt lgkmcnt(0)
	v_mfma_f32_16x16x32_bf16 v[124:127], v[160:163], v[210:213], v[124:127]
	v_mfma_f32_16x16x32_bf16 v[120:123], v[168:171], v[210:213], v[120:123]
	v_mfma_f32_16x16x32_bf16 v[108:111], v[160:163], v[218:221], v[108:111]
	v_mfma_f32_16x16x32_bf16 v[104:107], v[168:171], v[218:221], v[104:107]
	v_mfma_f32_16x16x32_bf16 v[92:95], v[160:163], v[226:229], v[92:95]
	v_mfma_f32_16x16x32_bf16 v[88:91], v[168:171], v[226:229], v[88:91]
	v_mfma_f32_16x16x32_bf16 v[76:79], v[160:163], v[234:237], v[76:79]
	v_mfma_f32_16x16x32_bf16 v[72:75], v[168:171], v[234:237], v[72:75]
	v_mfma_f32_16x16x32_bf16 v[124:127], v[164:167], v[214:217], v[124:127]
	v_mfma_f32_16x16x32_bf16 v[120:123], v[186:189], v[214:217], v[120:123]
	v_mfma_f32_16x16x32_bf16 v[108:111], v[164:167], v[222:225], v[108:111]
	v_mfma_f32_16x16x32_bf16 v[104:107], v[186:189], v[222:225], v[104:107]
	v_mfma_f32_16x16x32_bf16 v[92:95], v[164:167], v[230:233], v[92:95]
	v_mfma_f32_16x16x32_bf16 v[88:91], v[186:189], v[230:233], v[88:91]
	v_mfma_f32_16x16x32_bf16 v[76:79], v[164:167], v[238:241], v[76:79]
	v_mfma_f32_16x16x32_bf16 v[72:75], v[186:189], v[238:241], v[72:75]
	v_mfma_f32_16x16x32_bf16 v[116:119], v[194:197], v[210:213], v[116:119]
	v_mfma_f32_16x16x32_bf16 v[112:115], v[202:205], v[210:213], v[112:115]
	v_mfma_f32_16x16x32_bf16 v[100:103], v[194:197], v[218:221], v[100:103]
	v_mfma_f32_16x16x32_bf16 v[96:99], v[202:205], v[218:221], v[96:99]
	v_mfma_f32_16x16x32_bf16 v[84:87], v[194:197], v[226:229], v[84:87]
	v_mfma_f32_16x16x32_bf16 v[80:83], v[202:205], v[226:229], v[80:83]
	v_mfma_f32_16x16x32_bf16 v[68:71], v[194:197], v[234:237], v[68:71]
	v_mfma_f32_16x16x32_bf16 v[64:67], v[202:205], v[234:237], v[64:67]
	v_mfma_f32_16x16x32_bf16 v[116:119], v[198:201], v[214:217], v[116:119]
	v_mfma_f32_16x16x32_bf16 v[112:115], v[206:209], v[214:217], v[112:115]
	v_mfma_f32_16x16x32_bf16 v[100:103], v[198:201], v[222:225], v[100:103]
	v_mfma_f32_16x16x32_bf16 v[96:99], v[206:209], v[222:225], v[96:99]
	v_mfma_f32_16x16x32_bf16 v[84:87], v[198:201], v[230:233], v[84:87]
	v_mfma_f32_16x16x32_bf16 v[80:83], v[206:209], v[230:233], v[80:83]
	v_mfma_f32_16x16x32_bf16 v[68:71], v[198:201], v[238:241], v[68:71]
	v_mfma_f32_16x16x32_bf16 v[64:67], v[206:209], v[238:241], v[64:67]
	s_setprio 0
	s_barrier
	s_add_i32 s78, s78, s28
	v_lshl_add_u64 v[172:173], s[22:23], 0, v[132:133]
	s_mov_b32 m0, s78
	ds_read_b128 v[210:213], v184 offset:16384
	ds_read_b128 v[214:217], v184 offset:17408
	ds_read_b128 v[218:221], v184 offset:18432
	ds_read_b128 v[222:225], v184 offset:19456
	ds_read_b128 v[226:229], v184 offset:20480
	ds_read_b128 v[230:233], v184 offset:21504
	ds_read_b128 v[234:237], v184 offset:22528
	ds_read_b128 v[238:241], v184 offset:23552
	global_load_lds_dwordx4 v[172:173], off
	s_add_i32 m0, s78, 0x2000
	s_add_u32 vcc_lo, s22, 0x80000
	v_lshl_add_u64 v[190:191], s[22:23], 0, v[128:129]
	s_addc_u32 vcc_hi, s23, 0
	s_add_i32 s4, s4, s28
	global_load_lds_dwordx4 v[190:191], off
	v_lshl_add_u64 v[244:245], s[40:41], 0, v[130:131]
	v_lshl_add_u64 v[242:243], s[40:41], 0, v[134:135]
	s_mov_b32 m0, s30
	s_nop 0
	global_load_lds_dwordx4 v[242:243], off
	s_mov_b32 m0, s34
	s_nop 0
	global_load_lds_dwordx4 v[244:245], off
	s_waitcnt vmcnt(6)
	s_waitcnt lgkmcnt(0)
	s_barrier
; #define PG8_STAGE(bufoff, gbase, voff) do { _Pragma("unroll") for (int _i = 0; _i < 2; ++_i) \
;         __builtin_amdgcn_global_load_lds((const unsigned*)((const char*)(gbase) + (voff)[_i]), (LAS unsigned*)(lds + (bufoff) + ldsw + _i * 8192), 16, 0, PG8_AUX); } while (0)
; #define PG8_LDA(dst, b, h) do { _Pragma("unroll") for (int m = 0; m < 4; ++m) _Pragma("unroll") for (int k = 0; k < 2; ++k) dst[m][k] = *(const LAS bf16x8*)(lds + PG8_SA(b, h) + aoff + m * 2048 + k * 1024); } while (0)
; #define PG8_LDB(dst, b, h) do { _Pragma("unroll") for (int n = 0; n < 2; ++n) _Pragma("unroll") for (int k = 0; k < 2; ++k) dst[n][k] = *(const LAS bf16x8*)(lds + PG8_SB(b, h) + boff + n * 2048 + k * 1024); } while (0)
; #define PG8_MMA(ai, bj, At, Bt) do { __builtin_amdgcn_s_setprio(1); _Pragma("unroll") for (int m = 0; m < 4; ++m) _Pragma("unroll") for (int n = 0; n < 2; ++n) _Pragma("unroll") for (int k = 0; k < 2; ++k) \
;         acc[ai][bj][m][n] = __builtin_amdgcn_mfma_f32_16x16x32_bf16(Bt[n][k], At[m][k], acc[ai][bj][m][n], 0, 0, 0); __builtin_amdgcn_s_setprio(0); } while (0)
; #define PG8_WAIT_V(n) asm volatile("s_waitcnt vmcnt(" #n ")" ::: "memory")
; #define PG8_WAIT_L(n) asm volatile("s_waitcnt lgkmcnt(" #n ")" ::: "memory")
; #define PG8_BAR __builtin_amdgcn_s_barrier()
; #define PG8_SCHED __builtin_amdgcn_sched_barrier(0)
; template <class Epi, class Sched>
; __device__ __forceinline__ void gemm_phase(LAS unsigned char* lds, const Gemm g, const Sched& S, const Epi& E) {
;     ...
;             PG8_WAIT_V(8); PG8_WAIT_L(0); PG8_BAR; PG8_MMA(1, 0, At, B0); PG8_MMA(1, 1, At, B1); PG8_BAR; PG8_SCHED;
;             PG8_LDB(B0, 1, 0); PG8_LDB(B1, 1, 1); PG8_SCHED; PG8_LDA(At, 1, 0); PG8_STAGE(PG8_SA(0, 1), a2 + hstepA, voffA);
;             PG8_WAIT_V(8); PG8_WAIT_L(0); PG8_BAR; PG8_MMA(0, 0, At, B0); PG8_MMA(0, 1, At, B1); PG8_BAR; PG8_SCHED;
	s_setprio 1
	s_waitcnt lgkmcnt(0)
	v_mfma_f32_16x16x32_bf16 v[60:63], v[160:163], v[210:213], v[60:63]
	v_mfma_f32_16x16x32_bf16 v[56:59], v[168:171], v[210:213], v[56:59]
	v_mfma_f32_16x16x32_bf16 v[44:47], v[160:163], v[218:221], v[44:47]
	v_mfma_f32_16x16x32_bf16 v[40:43], v[168:171], v[218:221], v[40:43]
	v_mfma_f32_16x16x32_bf16 v[28:31], v[160:163], v[226:229], v[28:31]
	v_mfma_f32_16x16x32_bf16 v[24:27], v[168:171], v[226:229], v[24:27]
	v_mfma_f32_16x16x32_bf16 v[12:15], v[160:163], v[234:237], v[12:15]
	v_mfma_f32_16x16x32_bf16 v[8:11], v[168:171], v[234:237], v[8:11]
	v_mfma_f32_16x16x32_bf16 v[60:63], v[164:167], v[214:217], v[60:63]
	v_mfma_f32_16x16x32_bf16 v[56:59], v[186:189], v[214:217], v[56:59]
	v_mfma_f32_16x16x32_bf16 v[44:47], v[164:167], v[222:225], v[44:47]
	v_mfma_f32_16x16x32_bf16 v[40:43], v[186:189], v[222:225], v[40:43]
	v_mfma_f32_16x16x32_bf16 v[28:31], v[164:167], v[230:233], v[28:31]
	v_mfma_f32_16x16x32_bf16 v[24:27], v[186:189], v[230:233], v[24:27]
	v_mfma_f32_16x16x32_bf16 v[12:15], v[164:167], v[238:241], v[12:15]
	v_mfma_f32_16x16x32_bf16 v[8:11], v[186:189], v[238:241], v[8:11]
	v_mfma_f32_16x16x32_bf16 v[52:55], v[194:197], v[210:213], v[52:55]
	v_mfma_f32_16x16x32_bf16 v[48:51], v[202:205], v[210:213], v[48:51]
	v_mfma_f32_16x16x32_bf16 v[36:39], v[194:197], v[218:221], v[36:39]
	v_mfma_f32_16x16x32_bf16 v[32:35], v[202:205], v[218:221], v[32:35]
	v_mfma_f32_16x16x32_bf16 v[20:23], v[194:197], v[226:229], v[20:23]
	v_mfma_f32_16x16x32_bf16 v[16:19], v[202:205], v[226:229], v[16:19]
	v_mfma_f32_16x16x32_bf16 v[4:7], v[194:197], v[234:237], v[4:7]
	v_mfma_f32_16x16x32_bf16 v[0:3], v[202:205], v[234:237], v[0:3]
	v_mfma_f32_16x16x32_bf16 v[52:55], v[198:201], v[214:217], v[52:55]
	v_mfma_f32_16x16x32_bf16 v[48:51], v[206:209], v[214:217], v[48:51]
	v_mfma_f32_16x16x32_bf16 v[36:39], v[198:201], v[222:225], v[36:39]
	v_mfma_f32_16x16x32_bf16 v[32:35], v[206:209], v[222:225], v[32:35]
	v_mfma_f32_16x16x32_bf16 v[20:23], v[198:201], v[230:233], v[20:23]
	v_mfma_f32_16x16x32_bf16 v[16:19], v[206:209], v[230:233], v[16:19]
	v_mfma_f32_16x16x32_bf16 v[4:7], v[198:201], v[238:241], v[4:7]
	v_mfma_f32_16x16x32_bf16 v[0:3], v[206:209], v[238:241], v[0:3]
	s_setprio 0
	s_barrier
	s_add_i32 s4, 0, 0x18000
	v_add_u32_e32 v136, s4, v182
	s_add_i32 s78, 0, 0x1c000
	ds_read_b128 v[160:163], v136
	ds_read_b128 v[164:167], v136 offset:1024
	ds_read_b128 v[168:171], v136 offset:2048
	ds_read_b128 v[186:189], v136 offset:3072
	v_add_u32_e32 v136, s78, v182
	ds_read_b128 v[194:197], v136
	ds_read_b128 v[198:201], v136 offset:1024
	ds_read_b128 v[202:205], v136 offset:2048
	ds_read_b128 v[206:209], v136 offset:3072
	s_add_u32 s40, s40, 0x80000
	s_addc_u32 s41, s41, 0
	s_mov_b32 m0, s36
	v_lshl_add_u64 v[246:247], s[40:41], 0, v[134:135]
	ds_read_b128 v[210:213], v184 offset:32768
	ds_read_b128 v[214:217], v184 offset:33792
	ds_read_b128 v[218:221], v184 offset:34816
	ds_read_b128 v[222:225], v184 offset:35840
	ds_read_b128 v[226:229], v184 offset:36864
	ds_read_b128 v[230:233], v184 offset:37888
	ds_read_b128 v[234:237], v184 offset:38912
	ds_read_b128 v[238:241], v184 offset:39936
	s_add_u32 s100, s22, 0x80000
	s_addc_u32 s101, s23, 0
	s_add_i32 m0, s28, 0x14000
	s_nop 0
	global_load_lds_dwordx4 v132, s[100:101]
	s_add_i32 m0, s28, 0x16000
	s_nop 0
	global_load_lds_dwordx4 v128, s[100:101]
	s_mov_b32 m0, s36
	s_nop 0
	global_load_lds_dwordx4 v[246:247], off
	v_lshl_add_u64 v[246:247], s[40:41], 0, v[130:131]
	s_mov_b32 m0, s60
	s_nop 0
	global_load_lds_dwordx4 v[246:247], off
	s_waitcnt vmcnt(8)
	s_waitcnt lgkmcnt(0)
	s_barrier
	s_setprio 1
	s_waitcnt lgkmcnt(0)
	v_mfma_f32_16x16x32_bf16 v[124:127], v[160:163], v[210:213], v[124:127]
	v_mfma_f32_16x16x32_bf16 v[120:123], v[168:171], v[210:213], v[120:123]
	v_mfma_f32_16x16x32_bf16 v[108:111], v[160:163], v[218:221], v[108:111]
	v_mfma_f32_16x16x32_bf16 v[104:107], v[168:171], v[218:221], v[104:107]
	v_mfma_f32_16x16x32_bf16 v[92:95], v[160:163], v[226:229], v[92:95]
	v_mfma_f32_16x16x32_bf16 v[88:91], v[168:171], v[226:229], v[88:91]
	v_mfma_f32_16x16x32_bf16 v[76:79], v[160:163], v[234:237], v[76:79]
	v_mfma_f32_16x16x32_bf16 v[72:75], v[168:171], v[234:237], v[72:75]
	v_mfma_f32_16x16x32_bf16 v[124:127], v[164:167], v[214:217], v[124:127]
	v_mfma_f32_16x16x32_bf16 v[120:123], v[186:189], v[214:217], v[120:123]
	v_mfma_f32_16x16x32_bf16 v[108:111], v[164:167], v[222:225], v[108:111]
	v_mfma_f32_16x16x32_bf16 v[104:107], v[186:189], v[222:225], v[104:107]
	v_mfma_f32_16x16x32_bf16 v[92:95], v[164:167], v[230:233], v[92:95]
	v_mfma_f32_16x16x32_bf16 v[88:91], v[186:189], v[230:233], v[88:91]
	v_mfma_f32_16x16x32_bf16 v[76:79], v[164:167], v[238:241], v[76:79]
	v_mfma_f32_16x16x32_bf16 v[72:75], v[186:189], v[238:241], v[72:75]
	v_mfma_f32_16x16x32_bf16 v[116:119], v[194:197], v[210:213], v[116:119]
	v_mfma_f32_16x16x32_bf16 v[112:115], v[202:205], v[210:213], v[112:115]
	v_mfma_f32_16x16x32_bf16 v[100:103], v[194:197], v[218:221], v[100:103]
	v_mfma_f32_16x16x32_bf16 v[96:99], v[202:205], v[218:221], v[96:99]
	v_mfma_f32_16x16x32_bf16 v[84:87], v[194:197], v[226:229], v[84:87]
	v_mfma_f32_16x16x32_bf16 v[80:83], v[202:205], v[226:229], v[80:83]
	v_mfma_f32_16x16x32_bf16 v[68:71], v[194:197], v[234:237], v[68:71]
	v_mfma_f32_16x16x32_bf16 v[64:67], v[202:205], v[234:237], v[64:67]
	v_mfma_f32_16x16x32_bf16 v[116:119], v[198:201], v[214:217], v[116:119]
	v_mfma_f32_16x16x32_bf16 v[112:115], v[206:209], v[214:217], v[112:115]
	v_mfma_f32_16x16x32_bf16 v[100:103], v[198:201], v[222:225], v[100:103]
	v_mfma_f32_16x16x32_bf16 v[96:99], v[206:209], v[222:225], v[96:99]
	v_mfma_f32_16x16x32_bf16 v[84:87], v[198:201], v[230:233], v[84:87]
	v_mfma_f32_16x16x32_bf16 v[80:83], v[206:209], v[230:233], v[80:83]
	v_mfma_f32_16x16x32_bf16 v[68:71], v[198:201], v[238:241], v[68:71]
	v_mfma_f32_16x16x32_bf16 v[64:67], v[206:209], v[238:241], v[64:67]
	s_setprio 0
	s_barrier
; #define PG8_STAGE(bufoff, gbase, voff) do { _Pragma("unroll") for (int _i = 0; _i < 2; ++_i) \
;         __builtin_amdgcn_global_load_lds((const unsigned*)((const char*)(gbase) + (voff)[_i]), (LAS unsigned*)(lds + (bufoff) + ldsw + _i * 8192), 16, 0, PG8_AUX); } while (0)
; #define PG8_LDA(dst, b, h) do { _Pragma("unroll") for (int m = 0; m < 4; ++m) _Pragma("unroll") for (int k = 0; k < 2; ++k) dst[m][k] = *(const LAS bf16x8*)(lds + PG8_SA(b, h) + aoff + m * 2048 + k * 1024); } while (0)
; #define PG8_MMA(ai, bj, At, Bt) do { __builtin_amdgcn_s_setprio(1); _Pragma("unroll") for (int m = 0; m < 4; ++m) _Pragma("unroll") for (int n = 0; n < 2; ++n) _Pragma("unroll") for (int k = 0; k < 2; ++k) \
;         acc[ai][bj][m][n] = __builtin_amdgcn_mfma_f32_16x16x32_bf16(Bt[n][k], At[m][k], acc[ai][bj][m][n], 0, 0, 0); __builtin_amdgcn_s_setprio(0); } while (0)
; #define PG8_WAIT_V(n) asm volatile("s_waitcnt vmcnt(" #n ")" ::: "memory")
; #define PG8_WAIT_L(n) asm volatile("s_waitcnt lgkmcnt(" #n ")" ::: "memory")
; #define PG8_BAR __builtin_amdgcn_s_barrier()
; #define PG8_SCHED __builtin_amdgcn_sched_barrier(0)
; template <class Epi, class Sched>
; __device__ __forceinline__ void gemm_phase(LAS unsigned char* lds, const Gemm g, const Sched& S, const Epi& E) {
;     ...
;         for (int t = 0; t < nt; t += 2) {
;     ...
;             PG8_LDA(At, 1, 1); PG8_STAGE(PG8_SB(1, 0), b3, voffB); PG8_STAGE(PG8_SB(1, 1), b3 + hstepB, voffB); PG8_STAGE(PG8_SA(1, 0), a3, voffA);
;             PG8_WAIT_V(8); PG8_WAIT_L(0); PG8_BAR; PG8_MMA(1, 0, At, B0); PG8_MMA(1, 1, At, B1); PG8_BAR; PG8_SCHED;
	s_add_i32 s4, s4, s28
	v_lshl_add_u64 v[172:173], v[172:173], 0, s[12:13]
	s_mov_b32 m0, s4
	ds_read_b128 v[210:213], v184 offset:49152
	ds_read_b128 v[214:217], v184 offset:50176
	ds_read_b128 v[218:221], v184 offset:51200
	ds_read_b128 v[222:225], v184 offset:52224
	ds_read_b128 v[226:229], v184 offset:53248
	ds_read_b128 v[230:233], v184 offset:54272
	ds_read_b128 v[234:237], v184 offset:55296
	ds_read_b128 v[238:241], v184 offset:56320
	global_load_lds_dwordx4 v[172:173], off
	s_add_i32 m0, s4, 0x2000
	s_add_u32 s22, s22, 0x80080
	v_lshl_add_u64 v[172:173], v[190:191], 0, s[12:13]
	s_addc_u32 s23, s23, 0
	s_add_i32 s4, s78, s28
	global_load_lds_dwordx4 v[172:173], off
	v_lshl_add_u64 v[172:173], s[22:23], 0, v[132:133]
	s_mov_b32 m0, s4
	s_nop 0
	global_load_lds_dwordx4 v[172:173], off
	v_lshl_add_u64 v[172:173], s[22:23], 0, v[128:129]
	s_add_i32 m0, s4, 0x2000
	s_nop 0
	global_load_lds_dwordx4 v[172:173], off
	v_lshl_add_u64 v[172:173], v[242:243], 0, s[12:13]
	s_mov_b32 m0, s61
	s_nop 0
	global_load_lds_dwordx4 v[172:173], off
	v_lshl_add_u64 v[172:173], v[244:245], 0, s[12:13]
	s_mov_b32 m0, s62
	s_nop 0
	global_load_lds_dwordx4 v[172:173], off
	s_waitcnt vmcnt(8)
	s_waitcnt lgkmcnt(0)
	s_barrier
	s_setprio 1
	s_waitcnt lgkmcnt(0)
	v_mfma_f32_16x16x32_bf16 v[60:63], v[160:163], v[210:213], v[60:63]
	v_mfma_f32_16x16x32_bf16 v[56:59], v[168:171], v[210:213], v[56:59]
	v_mfma_f32_16x16x32_bf16 v[44:47], v[160:163], v[218:221], v[44:47]
	v_mfma_f32_16x16x32_bf16 v[40:43], v[168:171], v[218:221], v[40:43]
	v_mfma_f32_16x16x32_bf16 v[28:31], v[160:163], v[226:229], v[28:31]
	v_mfma_f32_16x16x32_bf16 v[24:27], v[168:171], v[226:229], v[24:27]
	v_mfma_f32_16x16x32_bf16 v[12:15], v[160:163], v[234:237], v[12:15]
	v_mfma_f32_16x16x32_bf16 v[8:11], v[168:171], v[234:237], v[8:11]
	v_mfma_f32_16x16x32_bf16 v[60:63], v[164:167], v[214:217], v[60:63]
	v_mfma_f32_16x16x32_bf16 v[56:59], v[186:189], v[214:217], v[56:59]
	v_mfma_f32_16x16x32_bf16 v[44:47], v[164:167], v[222:225], v[44:47]
	v_mfma_f32_16x16x32_bf16 v[40:43], v[186:189], v[222:225], v[40:43]
	v_mfma_f32_16x16x32_bf16 v[28:31], v[164:167], v[230:233], v[28:31]
	v_mfma_f32_16x16x32_bf16 v[24:27], v[186:189], v[230:233], v[24:27]
	v_mfma_f32_16x16x32_bf16 v[12:15], v[164:167], v[238:241], v[12:15]
	v_mfma_f32_16x16x32_bf16 v[8:11], v[186:189], v[238:241], v[8:11]
	v_mfma_f32_16x16x32_bf16 v[52:55], v[194:197], v[210:213], v[52:55]
	v_mfma_f32_16x16x32_bf16 v[48:51], v[202:205], v[210:213], v[48:51]
	v_mfma_f32_16x16x32_bf16 v[36:39], v[194:197], v[218:221], v[36:39]
	v_mfma_f32_16x16x32_bf16 v[32:35], v[202:205], v[218:221], v[32:35]
	v_mfma_f32_16x16x32_bf16 v[20:23], v[194:197], v[226:229], v[20:23]
	v_mfma_f32_16x16x32_bf16 v[16:19], v[202:205], v[226:229], v[16:19]
	v_mfma_f32_16x16x32_bf16 v[4:7], v[194:197], v[234:237], v[4:7]
	v_mfma_f32_16x16x32_bf16 v[0:3], v[202:205], v[234:237], v[0:3]
	v_mfma_f32_16x16x32_bf16 v[52:55], v[198:201], v[214:217], v[52:55]
	v_mfma_f32_16x16x32_bf16 v[48:51], v[206:209], v[214:217], v[48:51]
	v_mfma_f32_16x16x32_bf16 v[36:39], v[198:201], v[222:225], v[36:39]
	v_mfma_f32_16x16x32_bf16 v[32:35], v[206:209], v[222:225], v[32:35]
	v_mfma_f32_16x16x32_bf16 v[20:23], v[198:201], v[230:233], v[20:23]
	v_mfma_f32_16x16x32_bf16 v[16:19], v[206:209], v[230:233], v[16:19]
	v_mfma_f32_16x16x32_bf16 v[4:7], v[198:201], v[238:241], v[4:7]
	v_mfma_f32_16x16x32_bf16 v[0:3], v[206:209], v[238:241], v[0:3]
	s_setprio 0
	s_barrier
	s_add_i32 s65, s65, 2
	s_add_u32 s0, s0, 0x100
	s_addc_u32 s1, s1, 0
	s_add_u32 s63, s63, 0x100
	s_addc_u32 s64, s64, 0
	s_cmp_gt_u32 s65, 29
	s_cbranch_scc0 .LBB0_382
	s_and_b64 vcc, exec, s[46:47]
	s_cbranch_vccz .LBB0_385
	s_barrier

; #define PG8_STAGE(bufoff, gbase, voff) do { _Pragma("unroll") for (int _i = 0; _i < 2; ++_i) \
;         __builtin_amdgcn_global_load_lds((const unsigned*)((const char*)(gbase) + (voff)[_i]), (LAS unsigned*)(lds + (bufoff) + ldsw + _i * 8192), 16, 0, PG8_AUX); } while (0)
; #define PG8_LDA(dst, b, h) do { _Pragma("unroll") for (int m = 0; m < 4; ++m) _Pragma("unroll") for (int k = 0; k < 2; ++k) dst[m][k] = *(const LAS bf16x8*)(lds + PG8_SA(b, h) + aoff + m * 2048 + k * 1024); } while (0)
; #define PG8_LDB(dst, b, h) do { _Pragma("unroll") for (int n = 0; n < 2; ++n) _Pragma("unroll") for (int k = 0; k < 2; ++k) dst[n][k] = *(const LAS bf16x8*)(lds + PG8_SB(b, h) + boff + n * 2048 + k * 1024); } while (0)
; #define PG8_MMA(ai, bj, At, Bt) do { __builtin_amdgcn_s_setprio(1); _Pragma("unroll") for (int m = 0; m < 4; ++m) _Pragma("unroll") for (int n = 0; n < 2; ++n) _Pragma("unroll") for (int k = 0; k < 2; ++k) \
;         acc[ai][bj][m][n] = __builtin_amdgcn_mfma_f32_16x16x32_bf16(Bt[n][k], At[m][k], acc[ai][bj][m][n], 0, 0, 0); __builtin_amdgcn_s_setprio(0); } while (0)
; #define PG8_WAIT_V(n) asm volatile("s_waitcnt vmcnt(" #n ")" ::: "memory")
; #define PG8_WAIT_L(n) asm volatile("s_waitcnt lgkmcnt(" #n ")" ::: "memory")
; #define PG8_BAR __builtin_amdgcn_s_barrier()
; #define PG8_SCHED __builtin_amdgcn_sched_barrier(0)
; template <class Epi, class Sched>
; __device__ __forceinline__ void gemm_phase(LAS unsigned char* lds, const Gemm g, const Sched& S, const Epi& E) {
;     ...
;         for (int t = 0; t < nt; t += 2) {
;             const bool last = (t == nt - 2);
;             const char* a1 = cA + (size_t)(t + 1) * kstep;
;             const char* a2 = last ? nA : cA + (size_t)(t + 2) * kstep; const char* b2 = last ? nB : cB + (size_t)(t + 2) * kstep;
;             const char* a3 = a2 + kstep; const char* b3 = b2 + kstep;
;     ...
;             PG8_LDB(B0, 0, 0); PG8_LDB(B1, 0, 1); PG8_SCHED; PG8_LDA(At, 0, 0); PG8_STAGE(PG8_SA(1, 1), a1 + hstepA, voffA);
;             PG8_WAIT_V(8); PG8_WAIT_L(0); PG8_BAR; PG8_MMA(0, 0, At, B0); PG8_MMA(0, 1, At, B1); PG8_BAR; PG8_SCHED;
;             PG8_LDA(At, 0, 1); PG8_STAGE(PG8_SB(0, 0), b2, voffB); PG8_STAGE(PG8_SB(0, 1), b2 + hstepB, voffB); PG8_STAGE(PG8_SA(0, 0), a2, voffA);
;             PG8_WAIT_V(8); PG8_WAIT_L(0); PG8_BAR; PG8_MMA(1, 0, At, B0); PG8_MMA(1, 1, At, B1); PG8_BAR; PG8_SCHED;
.LBB0_679:
	s_add_u32 s54, s42, 0x100
	s_addc_u32 s55, s43, 0
	s_add_i32 s78, 0, 0x10000
	s_cmpk_eq_i32 s4, 0x54
	s_cselect_b32 s63, s1, s55
	s_cselect_b32 s62, s0, s54
	v_add_u32_e32 v164, s78, v167
	s_cselect_b32 s57, s53, vcc_hi
	s_cselect_b32 s56, s52, vcc_lo
	s_add_i32 s79, 0, 0x14000
	ds_read_b128 v[156:159], v164
	ds_read_b128 v[160:163], v164 offset:1024
	ds_read_b128 v[170:173], v164 offset:2048
	ds_read_b128 v[182:185], v164 offset:3072
	v_add_u32_e32 v164, s79, v167
	ds_read_b128 v[186:189], v164
	ds_read_b128 v[194:197], v164 offset:1024
	ds_read_b128 v[198:201], v164 offset:2048
	ds_read_b128 v[202:205], v164 offset:3072
	v_lshl_add_u64 v[164:165], s[42:43], 0, v[134:135]
	s_add_i32 m0, s36, 0xc000
	ds_read_b128 v[206:209], v169
	ds_read_b128 v[210:213], v169 offset:1024
	ds_read_b128 v[214:217], v169 offset:2048
	ds_read_b128 v[218:221], v169 offset:3072
	ds_read_b128 v[222:225], v169 offset:4096
	ds_read_b128 v[226:229], v169 offset:5120
	ds_read_b128 v[230:233], v169 offset:6144
	ds_read_b128 v[234:237], v169 offset:7168
	global_load_lds_dwordx4 v[164:165], off
	v_lshl_add_u64 v[164:165], s[42:43], 0, v[154:155]
	s_add_i32 m0, s36, 0xe000
	s_nop 0
	global_load_lds_dwordx4 v[164:165], off
	s_waitcnt vmcnt(8)
	s_waitcnt lgkmcnt(0)
	s_barrier
	s_setprio 1
	s_waitcnt lgkmcnt(0)
	v_mfma_f32_16x16x32_bf16 v[124:127], v[156:159], v[206:209], v[124:127]
	v_mfma_f32_16x16x32_bf16 v[120:123], v[170:173], v[206:209], v[120:123]
	v_mfma_f32_16x16x32_bf16 v[108:111], v[156:159], v[214:217], v[108:111]
	v_mfma_f32_16x16x32_bf16 v[104:107], v[170:173], v[214:217], v[104:107]
	v_mfma_f32_16x16x32_bf16 v[92:95], v[156:159], v[222:225], v[92:95]
	v_mfma_f32_16x16x32_bf16 v[88:91], v[170:173], v[222:225], v[88:91]
	v_mfma_f32_16x16x32_bf16 v[76:79], v[156:159], v[230:233], v[76:79]
	v_mfma_f32_16x16x32_bf16 v[72:75], v[170:173], v[230:233], v[72:75]
	v_mfma_f32_16x16x32_bf16 v[124:127], v[160:163], v[210:213], v[124:127]
	v_mfma_f32_16x16x32_bf16 v[120:123], v[182:185], v[210:213], v[120:123]
	v_mfma_f32_16x16x32_bf16 v[108:111], v[160:163], v[218:221], v[108:111]
	v_mfma_f32_16x16x32_bf16 v[104:107], v[182:185], v[218:221], v[104:107]
	v_mfma_f32_16x16x32_bf16 v[92:95], v[160:163], v[226:229], v[92:95]
	v_mfma_f32_16x16x32_bf16 v[88:91], v[182:185], v[226:229], v[88:91]
	v_mfma_f32_16x16x32_bf16 v[76:79], v[160:163], v[234:237], v[76:79]
	v_mfma_f32_16x16x32_bf16 v[72:75], v[182:185], v[234:237], v[72:75]
	v_mfma_f32_16x16x32_bf16 v[116:119], v[186:189], v[206:209], v[116:119]
	v_mfma_f32_16x16x32_bf16 v[112:115], v[198:201], v[206:209], v[112:115]
	v_mfma_f32_16x16x32_bf16 v[100:103], v[186:189], v[214:217], v[100:103]
	v_mfma_f32_16x16x32_bf16 v[96:99], v[198:201], v[214:217], v[96:99]
	v_mfma_f32_16x16x32_bf16 v[84:87], v[186:189], v[222:225], v[84:87]
	v_mfma_f32_16x16x32_bf16 v[80:83], v[198:201], v[222:225], v[80:83]
	v_mfma_f32_16x16x32_bf16 v[68:71], v[186:189], v[230:233], v[68:71]
	v_mfma_f32_16x16x32_bf16 v[64:67], v[198:201], v[230:233], v[64:67]
	v_mfma_f32_16x16x32_bf16 v[116:119], v[194:197], v[210:213], v[116:119]
	v_mfma_f32_16x16x32_bf16 v[112:115], v[202:205], v[210:213], v[112:115]
	v_mfma_f32_16x16x32_bf16 v[100:103], v[194:197], v[218:221], v[100:103]
	v_mfma_f32_16x16x32_bf16 v[96:99], v[202:205], v[218:221], v[96:99]
	v_mfma_f32_16x16x32_bf16 v[84:87], v[194:197], v[226:229], v[84:87]
	v_mfma_f32_16x16x32_bf16 v[80:83], v[202:205], v[226:229], v[80:83]
	v_mfma_f32_16x16x32_bf16 v[68:71], v[194:197], v[234:237], v[68:71]
	v_mfma_f32_16x16x32_bf16 v[64:67], v[202:205], v[234:237], v[64:67]
	s_setprio 0
	s_barrier
	s_add_i32 s42, s78, s34
	v_lshl_add_u64 v[164:165], s[56:57], 0, v[136:137]
	s_mov_b32 m0, s42
	ds_read_b128 v[206:209], v169 offset:16384
	ds_read_b128 v[210:213], v169 offset:17408
	ds_read_b128 v[214:217], v169 offset:18432
	ds_read_b128 v[218:221], v169 offset:19456
	ds_read_b128 v[222:225], v169 offset:20480
	ds_read_b128 v[226:229], v169 offset:21504
	ds_read_b128 v[230:233], v169 offset:22528
	ds_read_b128 v[234:237], v169 offset:23552
	global_load_lds_dwordx4 v[164:165], off
	s_add_i32 m0, s42, 0x2000
	s_add_u32 s42, s56, 0x160000
	v_lshl_add_u64 v[190:191], s[56:57], 0, v[128:129]
	s_addc_u32 s43, s57, 0
	s_add_i32 s78, s79, s34
	global_load_lds_dwordx4 v[190:191], off
	v_lshl_add_u64 v[238:239], s[42:43], 0, v[136:137]
	s_mov_b32 m0, s78
	v_lshl_add_u64 v[240:241], s[62:63], 0, v[130:131]
	global_load_lds_dwordx4 v[238:239], off
	v_lshl_add_u64 v[238:239], s[42:43], 0, v[128:129]
	s_add_i32 m0, s78, 0x2000
	s_nop 0
	global_load_lds_dwordx4 v[238:239], off
	v_lshl_add_u64 v[238:239], s[62:63], 0, v[132:133]
	s_mov_b32 m0, s36
	s_nop 0
	global_load_lds_dwordx4 v[238:239], off
	s_mov_b32 m0, s64
	s_nop 0
	global_load_lds_dwordx4 v[240:241], off
	s_waitcnt vmcnt(8)
	s_waitcnt lgkmcnt(0)
	s_barrier
; #define PG8_STAGE(bufoff, gbase, voff) do { _Pragma("unroll") for (int _i = 0; _i < 2; ++_i) \
;         __builtin_amdgcn_global_load_lds((const unsigned*)((const char*)(gbase) + (voff)[_i]), (LAS unsigned*)(lds + (bufoff) + ldsw + _i * 8192), 16, 0, PG8_AUX); } while (0)
; #define PG8_LDA(dst, b, h) do { _Pragma("unroll") for (int m = 0; m < 4; ++m) _Pragma("unroll") for (int k = 0; k < 2; ++k) dst[m][k] = *(const LAS bf16x8*)(lds + PG8_SA(b, h) + aoff + m * 2048 + k * 1024); } while (0)
; #define PG8_LDB(dst, b, h) do { _Pragma("unroll") for (int n = 0; n < 2; ++n) _Pragma("unroll") for (int k = 0; k < 2; ++k) dst[n][k] = *(const LAS bf16x8*)(lds + PG8_SB(b, h) + boff + n * 2048 + k * 1024); } while (0)
; #define PG8_MMA(ai, bj, At, Bt) do { __builtin_amdgcn_s_setprio(1); _Pragma("unroll") for (int m = 0; m < 4; ++m) _Pragma("unroll") for (int n = 0; n < 2; ++n) _Pragma("unroll") for (int k = 0; k < 2; ++k) \
;         acc[ai][bj][m][n] = __builtin_amdgcn_mfma_f32_16x16x32_bf16(Bt[n][k], At[m][k], acc[ai][bj][m][n], 0, 0, 0); __builtin_amdgcn_s_setprio(0); } while (0)
; #define PG8_WAIT_V(n) asm volatile("s_waitcnt vmcnt(" #n ")" ::: "memory")
; #define PG8_WAIT_L(n) asm volatile("s_waitcnt lgkmcnt(" #n ")" ::: "memory")
; #define PG8_BAR __builtin_amdgcn_s_barrier()
; #define PG8_SCHED __builtin_amdgcn_sched_barrier(0)
; template <class Epi, class Sched>
; __device__ __forceinline__ void gemm_phase(LAS unsigned char* lds, const Gemm g, const Sched& S, const Epi& E) {
;     ...
;             PG8_WAIT_V(8); PG8_WAIT_L(0); PG8_BAR; PG8_MMA(1, 0, At, B0); PG8_MMA(1, 1, At, B1); PG8_BAR; PG8_SCHED;
;             PG8_LDB(B0, 1, 0); PG8_LDB(B1, 1, 1); PG8_SCHED; PG8_LDA(At, 1, 0); PG8_STAGE(PG8_SA(0, 1), a2 + hstepA, voffA);
;             PG8_WAIT_V(8); PG8_WAIT_L(0); PG8_BAR; PG8_MMA(0, 0, At, B0); PG8_MMA(0, 1, At, B1); PG8_BAR; PG8_SCHED;
	s_setprio 1
	s_waitcnt lgkmcnt(0)
	v_mfma_f32_16x16x32_bf16 v[60:63], v[156:159], v[206:209], v[60:63]
	v_mfma_f32_16x16x32_bf16 v[56:59], v[170:173], v[206:209], v[56:59]
	v_mfma_f32_16x16x32_bf16 v[44:47], v[156:159], v[214:217], v[44:47]
	v_mfma_f32_16x16x32_bf16 v[40:43], v[170:173], v[214:217], v[40:43]
	v_mfma_f32_16x16x32_bf16 v[28:31], v[156:159], v[222:225], v[28:31]
	v_mfma_f32_16x16x32_bf16 v[24:27], v[170:173], v[222:225], v[24:27]
	v_mfma_f32_16x16x32_bf16 v[12:15], v[156:159], v[230:233], v[12:15]
	v_mfma_f32_16x16x32_bf16 v[8:11], v[170:173], v[230:233], v[8:11]
	v_mfma_f32_16x16x32_bf16 v[60:63], v[160:163], v[210:213], v[60:63]
	v_mfma_f32_16x16x32_bf16 v[56:59], v[182:185], v[210:213], v[56:59]
	v_mfma_f32_16x16x32_bf16 v[44:47], v[160:163], v[218:221], v[44:47]
	v_mfma_f32_16x16x32_bf16 v[40:43], v[182:185], v[218:221], v[40:43]
	v_mfma_f32_16x16x32_bf16 v[28:31], v[160:163], v[226:229], v[28:31]
	v_mfma_f32_16x16x32_bf16 v[24:27], v[182:185], v[226:229], v[24:27]
	v_mfma_f32_16x16x32_bf16 v[12:15], v[160:163], v[234:237], v[12:15]
	v_mfma_f32_16x16x32_bf16 v[8:11], v[182:185], v[234:237], v[8:11]
	v_mfma_f32_16x16x32_bf16 v[52:55], v[186:189], v[206:209], v[52:55]
	v_mfma_f32_16x16x32_bf16 v[48:51], v[198:201], v[206:209], v[48:51]
	v_mfma_f32_16x16x32_bf16 v[36:39], v[186:189], v[214:217], v[36:39]
	v_mfma_f32_16x16x32_bf16 v[32:35], v[198:201], v[214:217], v[32:35]
	v_mfma_f32_16x16x32_bf16 v[20:23], v[186:189], v[222:225], v[20:23]
	v_mfma_f32_16x16x32_bf16 v[16:19], v[198:201], v[222:225], v[16:19]
	v_mfma_f32_16x16x32_bf16 v[4:7], v[186:189], v[230:233], v[4:7]
	v_mfma_f32_16x16x32_bf16 v[0:3], v[198:201], v[230:233], v[0:3]
	v_mfma_f32_16x16x32_bf16 v[52:55], v[194:197], v[210:213], v[52:55]
	v_mfma_f32_16x16x32_bf16 v[48:51], v[202:205], v[210:213], v[48:51]
	v_mfma_f32_16x16x32_bf16 v[36:39], v[194:197], v[218:221], v[36:39]
	v_mfma_f32_16x16x32_bf16 v[32:35], v[202:205], v[218:221], v[32:35]
	v_mfma_f32_16x16x32_bf16 v[20:23], v[194:197], v[226:229], v[20:23]
	v_mfma_f32_16x16x32_bf16 v[16:19], v[202:205], v[226:229], v[16:19]
	v_mfma_f32_16x16x32_bf16 v[4:7], v[194:197], v[234:237], v[4:7]
	v_mfma_f32_16x16x32_bf16 v[0:3], v[202:205], v[234:237], v[0:3]
	s_setprio 0
	s_barrier
	s_add_i32 s78, 0, 0x18000
	v_add_u32_e32 v181, s78, v167
	s_add_i32 s79, 0, 0x1c000
	ds_read_b128 v[156:159], v181
	ds_read_b128 v[160:163], v181 offset:1024
	ds_read_b128 v[170:173], v181 offset:2048
	ds_read_b128 v[182:185], v181 offset:3072
	v_add_u32_e32 v181, s79, v167
	ds_read_b128 v[186:189], v181
	ds_read_b128 v[194:197], v181 offset:1024
	ds_read_b128 v[198:201], v181 offset:2048
	ds_read_b128 v[202:205], v181 offset:3072
	s_add_u32 s42, s62, 0x160000
	s_addc_u32 s43, s63, 0
	s_mov_b32 m0, s65
	v_lshl_add_u64 v[242:243], s[42:43], 0, v[132:133]
	ds_read_b128 v[206:209], v169 offset:32768
	ds_read_b128 v[210:213], v169 offset:33792
	ds_read_b128 v[214:217], v169 offset:34816
	ds_read_b128 v[218:221], v169 offset:35840
	ds_read_b128 v[222:225], v169 offset:36864
	ds_read_b128 v[226:229], v169 offset:37888
	ds_read_b128 v[230:233], v169 offset:38912
	ds_read_b128 v[234:237], v169 offset:39936
	global_load_lds_dwordx4 v[242:243], off
	v_lshl_add_u64 v[242:243], s[42:43], 0, v[130:131]
	s_mov_b32 m0, s92
	s_nop 0
	global_load_lds_dwordx4 v[242:243], off
	s_waitcnt vmcnt(8)
	s_waitcnt lgkmcnt(0)
	s_barrier
	s_setprio 1
	s_waitcnt lgkmcnt(0)
	v_mfma_f32_16x16x32_bf16 v[124:127], v[156:159], v[206:209], v[124:127]
	v_mfma_f32_16x16x32_bf16 v[120:123], v[170:173], v[206:209], v[120:123]
	v_mfma_f32_16x16x32_bf16 v[108:111], v[156:159], v[214:217], v[108:111]
	v_mfma_f32_16x16x32_bf16 v[104:107], v[170:173], v[214:217], v[104:107]
	v_mfma_f32_16x16x32_bf16 v[92:95], v[156:159], v[222:225], v[92:95]
	v_mfma_f32_16x16x32_bf16 v[88:91], v[170:173], v[222:225], v[88:91]
	v_mfma_f32_16x16x32_bf16 v[76:79], v[156:159], v[230:233], v[76:79]
	v_mfma_f32_16x16x32_bf16 v[72:75], v[170:173], v[230:233], v[72:75]
	v_mfma_f32_16x16x32_bf16 v[124:127], v[160:163], v[210:213], v[124:127]
	v_mfma_f32_16x16x32_bf16 v[120:123], v[182:185], v[210:213], v[120:123]
	v_mfma_f32_16x16x32_bf16 v[108:111], v[160:163], v[218:221], v[108:111]
	v_mfma_f32_16x16x32_bf16 v[104:107], v[182:185], v[218:221], v[104:107]
	v_mfma_f32_16x16x32_bf16 v[92:95], v[160:163], v[226:229], v[92:95]
	v_mfma_f32_16x16x32_bf16 v[88:91], v[182:185], v[226:229], v[88:91]
	v_mfma_f32_16x16x32_bf16 v[76:79], v[160:163], v[234:237], v[76:79]
	v_mfma_f32_16x16x32_bf16 v[72:75], v[182:185], v[234:237], v[72:75]
	v_mfma_f32_16x16x32_bf16 v[116:119], v[186:189], v[206:209], v[116:119]
	v_mfma_f32_16x16x32_bf16 v[112:115], v[198:201], v[206:209], v[112:115]
	v_mfma_f32_16x16x32_bf16 v[100:103], v[186:189], v[214:217], v[100:103]
	v_mfma_f32_16x16x32_bf16 v[96:99], v[198:201], v[214:217], v[96:99]
	v_mfma_f32_16x16x32_bf16 v[84:87], v[186:189], v[222:225], v[84:87]
	v_mfma_f32_16x16x32_bf16 v[80:83], v[198:201], v[222:225], v[80:83]
	v_mfma_f32_16x16x32_bf16 v[68:71], v[186:189], v[230:233], v[68:71]
	v_mfma_f32_16x16x32_bf16 v[64:67], v[198:201], v[230:233], v[64:67]
	v_mfma_f32_16x16x32_bf16 v[116:119], v[194:197], v[210:213], v[116:119]
	v_mfma_f32_16x16x32_bf16 v[112:115], v[202:205], v[210:213], v[112:115]
	v_mfma_f32_16x16x32_bf16 v[100:103], v[194:197], v[218:221], v[100:103]
	v_mfma_f32_16x16x32_bf16 v[96:99], v[202:205], v[218:221], v[96:99]
	v_mfma_f32_16x16x32_bf16 v[84:87], v[194:197], v[226:229], v[84:87]
	v_mfma_f32_16x16x32_bf16 v[80:83], v[202:205], v[226:229], v[80:83]
	v_mfma_f32_16x16x32_bf16 v[68:71], v[194:197], v[234:237], v[68:71]
	v_mfma_f32_16x16x32_bf16 v[64:67], v[202:205], v[234:237], v[64:67]
	s_setprio 0
	s_barrier
; #define PG8_STAGE(bufoff, gbase, voff) do { _Pragma("unroll") for (int _i = 0; _i < 2; ++_i) \
;         __builtin_amdgcn_global_load_lds((const unsigned*)((const char*)(gbase) + (voff)[_i]), (LAS unsigned*)(lds + (bufoff) + ldsw + _i * 8192), 16, 0, PG8_AUX); } while (0)
; #define PG8_LDA(dst, b, h) do { _Pragma("unroll") for (int m = 0; m < 4; ++m) _Pragma("unroll") for (int k = 0; k < 2; ++k) dst[m][k] = *(const LAS bf16x8*)(lds + PG8_SA(b, h) + aoff + m * 2048 + k * 1024); } while (0)
; #define PG8_MMA(ai, bj, At, Bt) do { __builtin_amdgcn_s_setprio(1); _Pragma("unroll") for (int m = 0; m < 4; ++m) _Pragma("unroll") for (int n = 0; n < 2; ++n) _Pragma("unroll") for (int k = 0; k < 2; ++k) \
;         acc[ai][bj][m][n] = __builtin_amdgcn_mfma_f32_16x16x32_bf16(Bt[n][k], At[m][k], acc[ai][bj][m][n], 0, 0, 0); __builtin_amdgcn_s_setprio(0); } while (0)
; #define PG8_WAIT_V(n) asm volatile("s_waitcnt vmcnt(" #n ")" ::: "memory")
; #define PG8_WAIT_L(n) asm volatile("s_waitcnt lgkmcnt(" #n ")" ::: "memory")
; #define PG8_BAR __builtin_amdgcn_s_barrier()
; #define PG8_SCHED __builtin_amdgcn_sched_barrier(0)
; template <class Epi, class Sched>
; __device__ __forceinline__ void gemm_phase(LAS unsigned char* lds, const Gemm g, const Sched& S, const Epi& E) {
;     ...
;         for (int t = 0; t < nt; t += 2) {
;     ...
;             PG8_LDA(At, 1, 1); PG8_STAGE(PG8_SB(1, 0), b3, voffB); PG8_STAGE(PG8_SB(1, 1), b3 + hstepB, voffB); PG8_STAGE(PG8_SA(1, 0), a3, voffA);
;             PG8_WAIT_V(8); PG8_WAIT_L(0); PG8_BAR; PG8_MMA(1, 0, At, B0); PG8_MMA(1, 1, At, B1); PG8_BAR; PG8_SCHED;
	s_add_i32 s42, s78, s34
	v_lshl_add_u64 v[164:165], v[164:165], 0, s[12:13]
	s_mov_b32 m0, s42
	ds_read_b128 v[206:209], v169 offset:49152
	ds_read_b128 v[210:213], v169 offset:50176
	ds_read_b128 v[214:217], v169 offset:51200
	ds_read_b128 v[218:221], v169 offset:52224
	ds_read_b128 v[222:225], v169 offset:53248
	ds_read_b128 v[226:229], v169 offset:54272
	ds_read_b128 v[230:233], v169 offset:55296
	ds_read_b128 v[234:237], v169 offset:56320
	global_load_lds_dwordx4 v[164:165], off
	s_add_i32 m0, s42, 0x2000
	s_add_u32 s42, s56, 0x160080
	v_lshl_add_u64 v[164:165], v[190:191], 0, s[12:13]
	s_addc_u32 s43, s57, 0
	s_add_i32 s56, s79, s34
	global_load_lds_dwordx4 v[164:165], off
	v_lshl_add_u64 v[164:165], s[42:43], 0, v[136:137]
	s_mov_b32 m0, s56
	s_nop 0
	global_load_lds_dwordx4 v[164:165], off
	v_lshl_add_u64 v[164:165], s[42:43], 0, v[128:129]
	s_add_i32 m0, s56, 0x2000
	s_nop 0
	global_load_lds_dwordx4 v[164:165], off
	v_lshl_add_u64 v[164:165], v[238:239], 0, s[12:13]
	s_mov_b32 m0, s94
	s_nop 0
	global_load_lds_dwordx4 v[164:165], off
	v_lshl_add_u64 v[164:165], v[240:241], 0, s[12:13]
	s_mov_b32 m0, s96
	s_nop 0
	global_load_lds_dwordx4 v[164:165], off
	s_waitcnt vmcnt(8)
	s_waitcnt lgkmcnt(0)
	s_barrier
	s_setprio 1
	s_waitcnt lgkmcnt(0)
	v_mfma_f32_16x16x32_bf16 v[60:63], v[156:159], v[206:209], v[60:63]
	v_mfma_f32_16x16x32_bf16 v[56:59], v[170:173], v[206:209], v[56:59]
	v_mfma_f32_16x16x32_bf16 v[44:47], v[156:159], v[214:217], v[44:47]
	v_mfma_f32_16x16x32_bf16 v[40:43], v[170:173], v[214:217], v[40:43]
	v_mfma_f32_16x16x32_bf16 v[28:31], v[156:159], v[222:225], v[28:31]
	v_mfma_f32_16x16x32_bf16 v[24:27], v[170:173], v[222:225], v[24:27]
	v_mfma_f32_16x16x32_bf16 v[12:15], v[156:159], v[230:233], v[12:15]
	v_mfma_f32_16x16x32_bf16 v[8:11], v[170:173], v[230:233], v[8:11]
	v_mfma_f32_16x16x32_bf16 v[60:63], v[160:163], v[210:213], v[60:63]
	v_mfma_f32_16x16x32_bf16 v[56:59], v[182:185], v[210:213], v[56:59]
	v_mfma_f32_16x16x32_bf16 v[44:47], v[160:163], v[218:221], v[44:47]
	v_mfma_f32_16x16x32_bf16 v[40:43], v[182:185], v[218:221], v[40:43]
	v_mfma_f32_16x16x32_bf16 v[28:31], v[160:163], v[226:229], v[28:31]
	v_mfma_f32_16x16x32_bf16 v[24:27], v[182:185], v[226:229], v[24:27]
	v_mfma_f32_16x16x32_bf16 v[12:15], v[160:163], v[234:237], v[12:15]
	v_mfma_f32_16x16x32_bf16 v[8:11], v[182:185], v[234:237], v[8:11]
	v_mfma_f32_16x16x32_bf16 v[52:55], v[186:189], v[206:209], v[52:55]
	v_mfma_f32_16x16x32_bf16 v[48:51], v[198:201], v[206:209], v[48:51]
	v_mfma_f32_16x16x32_bf16 v[36:39], v[186:189], v[214:217], v[36:39]
	v_mfma_f32_16x16x32_bf16 v[32:35], v[198:201], v[214:217], v[32:35]
	v_mfma_f32_16x16x32_bf16 v[20:23], v[186:189], v[222:225], v[20:23]
	v_mfma_f32_16x16x32_bf16 v[16:19], v[198:201], v[222:225], v[16:19]
	v_mfma_f32_16x16x32_bf16 v[4:7], v[186:189], v[230:233], v[4:7]
	v_mfma_f32_16x16x32_bf16 v[0:3], v[198:201], v[230:233], v[0:3]
	v_mfma_f32_16x16x32_bf16 v[52:55], v[194:197], v[210:213], v[52:55]
	v_mfma_f32_16x16x32_bf16 v[48:51], v[202:205], v[210:213], v[48:51]
	v_mfma_f32_16x16x32_bf16 v[36:39], v[194:197], v[218:221], v[36:39]
	v_mfma_f32_16x16x32_bf16 v[32:35], v[202:205], v[218:221], v[32:35]
	v_mfma_f32_16x16x32_bf16 v[20:23], v[194:197], v[226:229], v[20:23]
	v_mfma_f32_16x16x32_bf16 v[16:19], v[202:205], v[226:229], v[16:19]
	v_mfma_f32_16x16x32_bf16 v[4:7], v[194:197], v[234:237], v[4:7]
	v_mfma_f32_16x16x32_bf16 v[0:3], v[202:205], v[234:237], v[0:3]
	s_setprio 0
	s_barrier
	s_add_i32 s4, s4, 2
	s_add_u32 vcc_lo, vcc_lo, 0x100
	s_addc_u32 vcc_hi, vcc_hi, 0
	s_cmpk_gt_u32 s4, 0x55
	s_mov_b64 s[42:43], s[54:55]
	s_cbranch_scc0 .LBB0_679
	s_and_b64 vcc, exec, s[50:51]
	s_cbranch_vccz .LBB0_682
	s_barrier

; #define PG8_STAGE(bufoff, gbase, voff) do { _Pragma("unroll") for (int _i = 0; _i < 2; ++_i) \
;         __builtin_amdgcn_global_load_lds((const unsigned*)((const char*)(gbase) + (voff)[_i]), (LAS unsigned*)(lds + (bufoff) + ldsw + _i * 8192), 16, 0, PG8_AUX); } while (0)
; #define PG8_LDA(dst, b, h) do { _Pragma("unroll") for (int m = 0; m < 4; ++m) _Pragma("unroll") for (int k = 0; k < 2; ++k) dst[m][k] = *(const LAS bf16x8*)(lds + PG8_SA(b, h) + aoff + m * 2048 + k * 1024); } while (0)
; #define PG8_LDB(dst, b, h) do { _Pragma("unroll") for (int n = 0; n < 2; ++n) _Pragma("unroll") for (int k = 0; k < 2; ++k) dst[n][k] = *(const LAS bf16x8*)(lds + PG8_SB(b, h) + boff + n * 2048 + k * 1024); } while (0)
; #define PG8_MMA(ai, bj, At, Bt) do { __builtin_amdgcn_s_setprio(1); _Pragma("unroll") for (int m = 0; m < 4; ++m) _Pragma("unroll") for (int n = 0; n < 2; ++n) _Pragma("unroll") for (int k = 0; k < 2; ++k) \
;         acc[ai][bj][m][n] = __builtin_amdgcn_mfma_f32_16x16x32_bf16(Bt[n][k], At[m][k], acc[ai][bj][m][n], 0, 0, 0); __builtin_amdgcn_s_setprio(0); } while (0)
; #define PG8_WAIT_V(n) asm volatile("s_waitcnt vmcnt(" #n ")" ::: "memory")
; #define PG8_WAIT_L(n) asm volatile("s_waitcnt lgkmcnt(" #n ")" ::: "memory")
; #define PG8_BAR __builtin_amdgcn_s_barrier()
; #define PG8_SCHED __builtin_amdgcn_sched_barrier(0)
; template <class Epi, class Sched>
; __device__ __forceinline__ void gemm_phase(LAS unsigned char* lds, const Gemm g, const Sched& S, const Epi& E) {
;     ...
;         for (int t = 0; t < nt; t += 2) {
;             const bool last = (t == nt - 2);
;             const char* a1 = cA + (size_t)(t + 1) * kstep;
;             const char* a2 = last ? nA : cA + (size_t)(t + 2) * kstep; const char* b2 = last ? nB : cB + (size_t)(t + 2) * kstep;
;             const char* a3 = a2 + kstep; const char* b3 = b2 + kstep;
;     ...
;             PG8_LDB(B0, 0, 0); PG8_LDB(B1, 0, 1); PG8_SCHED; PG8_LDA(At, 0, 0); PG8_STAGE(PG8_SA(1, 1), a1 + hstepA, voffA);
;             PG8_WAIT_V(8); PG8_WAIT_L(0); PG8_BAR; PG8_MMA(0, 0, At, B0); PG8_MMA(0, 1, At, B1); PG8_BAR; PG8_SCHED;
;             PG8_LDA(At, 0, 1); PG8_STAGE(PG8_SB(0, 0), b2, voffB); PG8_STAGE(PG8_SB(0, 1), b2 + hstepB, voffB); PG8_STAGE(PG8_SA(0, 0), a2, voffA);
;             PG8_WAIT_V(8); PG8_WAIT_L(0); PG8_BAR; PG8_MMA(1, 0, At, B0); PG8_MMA(1, 1, At, B1); PG8_BAR; PG8_SCHED;
.LBB0_745:
	s_add_u32 s4, s22, 0xfff80080
	s_addc_u32 s52, s23, -1
	s_add_i32 s78, 0, 0x10000
	s_cmp_eq_u32 s94, 28
	s_cselect_b32 s55, s45, s52
	s_cselect_b32 s54, s60, s4
	v_add_u32_e32 v160, s78, v163
	s_cselect_b32 s53, s47, s92
	s_cselect_b32 s52, s61, s65
	s_add_i32 s4, 0, 0x14000
	ds_read_b128 v[156:159], v160
	ds_read_b128 v[166:169], v160 offset:1024
	ds_read_b128 v[170:173], v160 offset:2048
	ds_read_b128 v[182:185], v160 offset:3072
	v_add_u32_e32 v160, s4, v163
	ds_read_b128 v[186:189], v160
	ds_read_b128 v[194:197], v160 offset:1024
	ds_read_b128 v[198:201], v160 offset:2048
	ds_read_b128 v[202:205], v160 offset:3072
	v_lshl_add_u64 v[160:161], s[22:23], 0, v[134:135]
	s_add_i32 m0, s36, 0xc000
	ds_read_b128 v[206:209], v165
	ds_read_b128 v[210:213], v165 offset:1024
	ds_read_b128 v[214:217], v165 offset:2048
	ds_read_b128 v[218:221], v165 offset:3072
	ds_read_b128 v[222:225], v165 offset:4096
	ds_read_b128 v[226:229], v165 offset:5120
	ds_read_b128 v[230:233], v165 offset:6144
	ds_read_b128 v[234:237], v165 offset:7168
	global_load_lds_dwordx4 v[160:161], off
	v_lshl_add_u64 v[160:161], s[22:23], 0, v[154:155]
	s_add_i32 m0, s36, 0xe000
	s_nop 0
	global_load_lds_dwordx4 v[160:161], off
	s_waitcnt vmcnt(8)
	s_waitcnt lgkmcnt(0)
	s_barrier
	s_setprio 1
	s_waitcnt lgkmcnt(0)
	v_mfma_f32_16x16x32_bf16 v[124:127], v[156:159], v[206:209], v[124:127]
	v_mfma_f32_16x16x32_bf16 v[116:119], v[170:173], v[206:209], v[116:119]
	v_mfma_f32_16x16x32_bf16 v[108:111], v[156:159], v[214:217], v[108:111]
	v_mfma_f32_16x16x32_bf16 v[100:103], v[170:173], v[214:217], v[100:103]
	v_mfma_f32_16x16x32_bf16 v[92:95], v[156:159], v[222:225], v[92:95]
	v_mfma_f32_16x16x32_bf16 v[84:87], v[170:173], v[222:225], v[84:87]
	v_mfma_f32_16x16x32_bf16 v[76:79], v[156:159], v[230:233], v[76:79]
	v_mfma_f32_16x16x32_bf16 v[68:71], v[170:173], v[230:233], v[68:71]
	v_mfma_f32_16x16x32_bf16 v[124:127], v[166:169], v[210:213], v[124:127]
	v_mfma_f32_16x16x32_bf16 v[116:119], v[182:185], v[210:213], v[116:119]
	v_mfma_f32_16x16x32_bf16 v[108:111], v[166:169], v[218:221], v[108:111]
	v_mfma_f32_16x16x32_bf16 v[100:103], v[182:185], v[218:221], v[100:103]
	v_mfma_f32_16x16x32_bf16 v[92:95], v[166:169], v[226:229], v[92:95]
	v_mfma_f32_16x16x32_bf16 v[84:87], v[182:185], v[226:229], v[84:87]
	v_mfma_f32_16x16x32_bf16 v[76:79], v[166:169], v[234:237], v[76:79]
	v_mfma_f32_16x16x32_bf16 v[68:71], v[182:185], v[234:237], v[68:71]
	v_mfma_f32_16x16x32_bf16 v[120:123], v[186:189], v[206:209], v[120:123]
	v_mfma_f32_16x16x32_bf16 v[112:115], v[198:201], v[206:209], v[112:115]
	v_mfma_f32_16x16x32_bf16 v[104:107], v[186:189], v[214:217], v[104:107]
	v_mfma_f32_16x16x32_bf16 v[96:99], v[198:201], v[214:217], v[96:99]
	v_mfma_f32_16x16x32_bf16 v[88:91], v[186:189], v[222:225], v[88:91]
	v_mfma_f32_16x16x32_bf16 v[80:83], v[198:201], v[222:225], v[80:83]
	v_mfma_f32_16x16x32_bf16 v[72:75], v[186:189], v[230:233], v[72:75]
	v_mfma_f32_16x16x32_bf16 v[64:67], v[198:201], v[230:233], v[64:67]
	v_mfma_f32_16x16x32_bf16 v[120:123], v[194:197], v[210:213], v[120:123]
	v_mfma_f32_16x16x32_bf16 v[112:115], v[202:205], v[210:213], v[112:115]
	v_mfma_f32_16x16x32_bf16 v[104:107], v[194:197], v[218:221], v[104:107]
	v_mfma_f32_16x16x32_bf16 v[96:99], v[202:205], v[218:221], v[96:99]
	v_mfma_f32_16x16x32_bf16 v[88:91], v[194:197], v[226:229], v[88:91]
	v_mfma_f32_16x16x32_bf16 v[80:83], v[202:205], v[226:229], v[80:83]
	v_mfma_f32_16x16x32_bf16 v[72:75], v[194:197], v[234:237], v[72:75]
	v_mfma_f32_16x16x32_bf16 v[64:67], v[202:205], v[234:237], v[64:67]
	s_setprio 0
	s_barrier
	s_add_i32 s78, s78, s34
	v_lshl_add_u64 v[160:161], s[52:53], 0, v[136:137]
	s_mov_b32 m0, s78
	ds_read_b128 v[206:209], v165 offset:16384
	ds_read_b128 v[210:213], v165 offset:17408
	ds_read_b128 v[214:217], v165 offset:18432
	ds_read_b128 v[218:221], v165 offset:19456
	ds_read_b128 v[222:225], v165 offset:20480
	ds_read_b128 v[226:229], v165 offset:21504
	ds_read_b128 v[230:233], v165 offset:22528
	ds_read_b128 v[234:237], v165 offset:23552
	global_load_lds_dwordx4 v[160:161], off
	s_add_i32 m0, s78, 0x2000
	s_add_u32 vcc_lo, s52, 0x80000
	v_lshl_add_u64 v[190:191], s[52:53], 0, v[128:129]
	s_addc_u32 vcc_hi, s53, 0
	s_add_i32 s4, s4, s34
	global_load_lds_dwordx4 v[190:191], off
	v_lshl_add_u64 v[240:241], s[54:55], 0, v[130:131]
	v_lshl_add_u64 v[238:239], s[54:55], 0, v[132:133]
	s_mov_b32 m0, s36
	s_nop 0
	global_load_lds_dwordx4 v[238:239], off
	s_mov_b32 m0, s56
	s_nop 0
	global_load_lds_dwordx4 v[240:241], off
	s_waitcnt vmcnt(6)
	s_waitcnt lgkmcnt(0)
	s_barrier
; #define PG8_STAGE(bufoff, gbase, voff) do { _Pragma("unroll") for (int _i = 0; _i < 2; ++_i) \
;         __builtin_amdgcn_global_load_lds((const unsigned*)((const char*)(gbase) + (voff)[_i]), (LAS unsigned*)(lds + (bufoff) + ldsw + _i * 8192), 16, 0, PG8_AUX); } while (0)
; #define PG8_LDA(dst, b, h) do { _Pragma("unroll") for (int m = 0; m < 4; ++m) _Pragma("unroll") for (int k = 0; k < 2; ++k) dst[m][k] = *(const LAS bf16x8*)(lds + PG8_SA(b, h) + aoff + m * 2048 + k * 1024); } while (0)
; #define PG8_LDB(dst, b, h) do { _Pragma("unroll") for (int n = 0; n < 2; ++n) _Pragma("unroll") for (int k = 0; k < 2; ++k) dst[n][k] = *(const LAS bf16x8*)(lds + PG8_SB(b, h) + boff + n * 2048 + k * 1024); } while (0)
; #define PG8_MMA(ai, bj, At, Bt) do { __builtin_amdgcn_s_setprio(1); _Pragma("unroll") for (int m = 0; m < 4; ++m) _Pragma("unroll") for (int n = 0; n < 2; ++n) _Pragma("unroll") for (int k = 0; k < 2; ++k) \
;         acc[ai][bj][m][n] = __builtin_amdgcn_mfma_f32_16x16x32_bf16(Bt[n][k], At[m][k], acc[ai][bj][m][n], 0, 0, 0); __builtin_amdgcn_s_setprio(0); } while (0)
; #define PG8_WAIT_V(n) asm volatile("s_waitcnt vmcnt(" #n ")" ::: "memory")
; #define PG8_WAIT_L(n) asm volatile("s_waitcnt lgkmcnt(" #n ")" ::: "memory")
; #define PG8_BAR __builtin_amdgcn_s_barrier()
; #define PG8_SCHED __builtin_amdgcn_sched_barrier(0)
; template <class Epi, class Sched>
; __device__ __forceinline__ void gemm_phase(LAS unsigned char* lds, const Gemm g, const Sched& S, const Epi& E) {
;     ...
;             PG8_WAIT_V(8); PG8_WAIT_L(0); PG8_BAR; PG8_MMA(1, 0, At, B0); PG8_MMA(1, 1, At, B1); PG8_BAR; PG8_SCHED;
;             PG8_LDB(B0, 1, 0); PG8_LDB(B1, 1, 1); PG8_SCHED; PG8_LDA(At, 1, 0); PG8_STAGE(PG8_SA(0, 1), a2 + hstepA, voffA);
;             PG8_WAIT_V(8); PG8_WAIT_L(0); PG8_BAR; PG8_MMA(0, 0, At, B0); PG8_MMA(0, 1, At, B1); PG8_BAR; PG8_SCHED;
	s_setprio 1
	s_waitcnt lgkmcnt(0)
	v_mfma_f32_16x16x32_bf16 v[60:63], v[156:159], v[206:209], v[60:63]
	v_mfma_f32_16x16x32_bf16 v[52:55], v[170:173], v[206:209], v[52:55]
	v_mfma_f32_16x16x32_bf16 v[44:47], v[156:159], v[214:217], v[44:47]
	v_mfma_f32_16x16x32_bf16 v[36:39], v[170:173], v[214:217], v[36:39]
	v_mfma_f32_16x16x32_bf16 v[28:31], v[156:159], v[222:225], v[28:31]
	v_mfma_f32_16x16x32_bf16 v[20:23], v[170:173], v[222:225], v[20:23]
	v_mfma_f32_16x16x32_bf16 v[12:15], v[156:159], v[230:233], v[12:15]
	v_mfma_f32_16x16x32_bf16 v[4:7], v[170:173], v[230:233], v[4:7]
	v_mfma_f32_16x16x32_bf16 v[60:63], v[166:169], v[210:213], v[60:63]
	v_mfma_f32_16x16x32_bf16 v[52:55], v[182:185], v[210:213], v[52:55]
	v_mfma_f32_16x16x32_bf16 v[44:47], v[166:169], v[218:221], v[44:47]
	v_mfma_f32_16x16x32_bf16 v[36:39], v[182:185], v[218:221], v[36:39]
	v_mfma_f32_16x16x32_bf16 v[28:31], v[166:169], v[226:229], v[28:31]
	v_mfma_f32_16x16x32_bf16 v[20:23], v[182:185], v[226:229], v[20:23]
	v_mfma_f32_16x16x32_bf16 v[12:15], v[166:169], v[234:237], v[12:15]
	v_mfma_f32_16x16x32_bf16 v[4:7], v[182:185], v[234:237], v[4:7]
	v_mfma_f32_16x16x32_bf16 v[56:59], v[186:189], v[206:209], v[56:59]
	v_mfma_f32_16x16x32_bf16 v[48:51], v[198:201], v[206:209], v[48:51]
	v_mfma_f32_16x16x32_bf16 v[40:43], v[186:189], v[214:217], v[40:43]
	v_mfma_f32_16x16x32_bf16 v[32:35], v[198:201], v[214:217], v[32:35]
	v_mfma_f32_16x16x32_bf16 v[24:27], v[186:189], v[222:225], v[24:27]
	v_mfma_f32_16x16x32_bf16 v[16:19], v[198:201], v[222:225], v[16:19]
	v_mfma_f32_16x16x32_bf16 v[8:11], v[186:189], v[230:233], v[8:11]
	v_mfma_f32_16x16x32_bf16 v[0:3], v[198:201], v[230:233], v[0:3]
	v_mfma_f32_16x16x32_bf16 v[56:59], v[194:197], v[210:213], v[56:59]
	v_mfma_f32_16x16x32_bf16 v[48:51], v[202:205], v[210:213], v[48:51]
	v_mfma_f32_16x16x32_bf16 v[40:43], v[194:197], v[218:221], v[40:43]
	v_mfma_f32_16x16x32_bf16 v[32:35], v[202:205], v[218:221], v[32:35]
	v_mfma_f32_16x16x32_bf16 v[24:27], v[194:197], v[226:229], v[24:27]
	v_mfma_f32_16x16x32_bf16 v[16:19], v[202:205], v[226:229], v[16:19]
	v_mfma_f32_16x16x32_bf16 v[8:11], v[194:197], v[234:237], v[8:11]
	v_mfma_f32_16x16x32_bf16 v[0:3], v[202:205], v[234:237], v[0:3]
	s_setprio 0
	s_barrier
	s_add_i32 s4, 0, 0x18000
	v_add_u32_e32 v181, s4, v163
	s_add_i32 s78, 0, 0x1c000
	ds_read_b128 v[156:159], v181
	ds_read_b128 v[166:169], v181 offset:1024
	ds_read_b128 v[170:173], v181 offset:2048
	ds_read_b128 v[182:185], v181 offset:3072
	v_add_u32_e32 v181, s78, v163
	ds_read_b128 v[186:189], v181
	ds_read_b128 v[194:197], v181 offset:1024
	ds_read_b128 v[198:201], v181 offset:2048
	ds_read_b128 v[202:205], v181 offset:3072
	s_add_u32 s54, s54, 0x80000
	s_addc_u32 s55, s55, 0
	s_mov_b32 m0, s57
	v_lshl_add_u64 v[242:243], s[54:55], 0, v[132:133]
	ds_read_b128 v[206:209], v165 offset:32768
	ds_read_b128 v[210:213], v165 offset:33792
	ds_read_b128 v[214:217], v165 offset:34816
	ds_read_b128 v[218:221], v165 offset:35840
	ds_read_b128 v[222:225], v165 offset:36864
	ds_read_b128 v[226:229], v165 offset:37888
	ds_read_b128 v[230:233], v165 offset:38912
	ds_read_b128 v[234:237], v165 offset:39936
	s_add_u32 s100, s52, 0x80000
	s_addc_u32 s101, s53, 0
	s_add_i32 m0, s34, 0x14000
	s_nop 0
	global_load_lds_dwordx4 v136, s[100:101]
	s_add_i32 m0, s34, 0x16000
	s_nop 0
	global_load_lds_dwordx4 v128, s[100:101]
	s_mov_b32 m0, s57
	s_nop 0
	global_load_lds_dwordx4 v[242:243], off
	v_lshl_add_u64 v[242:243], s[54:55], 0, v[130:131]
	s_mov_b32 m0, s62
	s_nop 0
	global_load_lds_dwordx4 v[242:243], off
	s_waitcnt vmcnt(8)
	s_waitcnt lgkmcnt(0)
	s_barrier
	s_setprio 1
	s_waitcnt lgkmcnt(0)
	v_mfma_f32_16x16x32_bf16 v[124:127], v[156:159], v[206:209], v[124:127]
	v_mfma_f32_16x16x32_bf16 v[116:119], v[170:173], v[206:209], v[116:119]
	v_mfma_f32_16x16x32_bf16 v[108:111], v[156:159], v[214:217], v[108:111]
	v_mfma_f32_16x16x32_bf16 v[100:103], v[170:173], v[214:217], v[100:103]
	v_mfma_f32_16x16x32_bf16 v[92:95], v[156:159], v[222:225], v[92:95]
	v_mfma_f32_16x16x32_bf16 v[84:87], v[170:173], v[222:225], v[84:87]
	v_mfma_f32_16x16x32_bf16 v[76:79], v[156:159], v[230:233], v[76:79]
	v_mfma_f32_16x16x32_bf16 v[68:71], v[170:173], v[230:233], v[68:71]
	v_mfma_f32_16x16x32_bf16 v[124:127], v[166:169], v[210:213], v[124:127]
	v_mfma_f32_16x16x32_bf16 v[116:119], v[182:185], v[210:213], v[116:119]
	v_mfma_f32_16x16x32_bf16 v[108:111], v[166:169], v[218:221], v[108:111]
	v_mfma_f32_16x16x32_bf16 v[100:103], v[182:185], v[218:221], v[100:103]
	v_mfma_f32_16x16x32_bf16 v[92:95], v[166:169], v[226:229], v[92:95]
	v_mfma_f32_16x16x32_bf16 v[84:87], v[182:185], v[226:229], v[84:87]
	v_mfma_f32_16x16x32_bf16 v[76:79], v[166:169], v[234:237], v[76:79]
	v_mfma_f32_16x16x32_bf16 v[68:71], v[182:185], v[234:237], v[68:71]
	v_mfma_f32_16x16x32_bf16 v[120:123], v[186:189], v[206:209], v[120:123]
	v_mfma_f32_16x16x32_bf16 v[112:115], v[198:201], v[206:209], v[112:115]
	v_mfma_f32_16x16x32_bf16 v[104:107], v[186:189], v[214:217], v[104:107]
	v_mfma_f32_16x16x32_bf16 v[96:99], v[198:201], v[214:217], v[96:99]
	v_mfma_f32_16x16x32_bf16 v[88:91], v[186:189], v[222:225], v[88:91]
	v_mfma_f32_16x16x32_bf16 v[80:83], v[198:201], v[222:225], v[80:83]
	v_mfma_f32_16x16x32_bf16 v[72:75], v[186:189], v[230:233], v[72:75]
	v_mfma_f32_16x16x32_bf16 v[64:67], v[198:201], v[230:233], v[64:67]
	v_mfma_f32_16x16x32_bf16 v[120:123], v[194:197], v[210:213], v[120:123]
	v_mfma_f32_16x16x32_bf16 v[112:115], v[202:205], v[210:213], v[112:115]
	v_mfma_f32_16x16x32_bf16 v[104:107], v[194:197], v[218:221], v[104:107]
	v_mfma_f32_16x16x32_bf16 v[96:99], v[202:205], v[218:221], v[96:99]
	v_mfma_f32_16x16x32_bf16 v[88:91], v[194:197], v[226:229], v[88:91]
	v_mfma_f32_16x16x32_bf16 v[80:83], v[202:205], v[226:229], v[80:83]
	v_mfma_f32_16x16x32_bf16 v[72:75], v[194:197], v[234:237], v[72:75]
	v_mfma_f32_16x16x32_bf16 v[64:67], v[202:205], v[234:237], v[64:67]
	s_setprio 0
	s_barrier
; #define PG8_STAGE(bufoff, gbase, voff) do { _Pragma("unroll") for (int _i = 0; _i < 2; ++_i) \
;         __builtin_amdgcn_global_load_lds((const unsigned*)((const char*)(gbase) + (voff)[_i]), (LAS unsigned*)(lds + (bufoff) + ldsw + _i * 8192), 16, 0, PG8_AUX); } while (0)
; #define PG8_LDA(dst, b, h) do { _Pragma("unroll") for (int m = 0; m < 4; ++m) _Pragma("unroll") for (int k = 0; k < 2; ++k) dst[m][k] = *(const LAS bf16x8*)(lds + PG8_SA(b, h) + aoff + m * 2048 + k * 1024); } while (0)
; #define PG8_MMA(ai, bj, At, Bt) do { __builtin_amdgcn_s_setprio(1); _Pragma("unroll") for (int m = 0; m < 4; ++m) _Pragma("unroll") for (int n = 0; n < 2; ++n) _Pragma("unroll") for (int k = 0; k < 2; ++k) \
;         acc[ai][bj][m][n] = __builtin_amdgcn_mfma_f32_16x16x32_bf16(Bt[n][k], At[m][k], acc[ai][bj][m][n], 0, 0, 0); __builtin_amdgcn_s_setprio(0); } while (0)
; #define PG8_WAIT_V(n) asm volatile("s_waitcnt vmcnt(" #n ")" ::: "memory")
; #define PG8_WAIT_L(n) asm volatile("s_waitcnt lgkmcnt(" #n ")" ::: "memory")
; #define PG8_BAR __builtin_amdgcn_s_barrier()
; #define PG8_SCHED __builtin_amdgcn_sched_barrier(0)
; template <class Epi, class Sched>
; __device__ __forceinline__ void gemm_phase(LAS unsigned char* lds, const Gemm g, const Sched& S, const Epi& E) {
;     ...
;             PG8_LDA(At, 1, 1); PG8_STAGE(PG8_SB(1, 0), b3, voffB); PG8_STAGE(PG8_SB(1, 1), b3 + hstepB, voffB); PG8_STAGE(PG8_SA(1, 0), a3, voffA);
;             PG8_WAIT_V(8); PG8_WAIT_L(0); PG8_BAR; PG8_MMA(1, 0, At, B0); PG8_MMA(1, 1, At, B1); PG8_BAR; PG8_SCHED;
	s_add_i32 s4, s4, s34
	v_lshl_add_u64 v[160:161], v[160:161], 0, s[12:13]
	s_mov_b32 m0, s4
	ds_read_b128 v[206:209], v165 offset:49152
	ds_read_b128 v[210:213], v165 offset:50176
	ds_read_b128 v[214:217], v165 offset:51200
	ds_read_b128 v[218:221], v165 offset:52224
	ds_read_b128 v[222:225], v165 offset:53248
	ds_read_b128 v[226:229], v165 offset:54272
	ds_read_b128 v[230:233], v165 offset:55296
	ds_read_b128 v[234:237], v165 offset:56320
	global_load_lds_dwordx4 v[160:161], off
	s_add_i32 m0, s4, 0x2000
	s_add_u32 s52, s52, 0x80080
	v_lshl_add_u64 v[160:161], v[190:191], 0, s[12:13]
	s_addc_u32 s53, s53, 0
	s_add_i32 s4, s78, s34
	global_load_lds_dwordx4 v[160:161], off
	v_lshl_add_u64 v[160:161], s[52:53], 0, v[136:137]
	s_mov_b32 m0, s4
	s_nop 0
	global_load_lds_dwordx4 v[160:161], off
	v_lshl_add_u64 v[160:161], s[52:53], 0, v[128:129]
	s_add_i32 m0, s4, 0x2000
	s_nop 0
	global_load_lds_dwordx4 v[160:161], off
	v_lshl_add_u64 v[160:161], v[238:239], 0, s[12:13]
	s_mov_b32 m0, s63
	s_nop 0
	global_load_lds_dwordx4 v[160:161], off
	v_lshl_add_u64 v[160:161], v[240:241], 0, s[12:13]
	s_mov_b32 m0, s64
	s_nop 0
	global_load_lds_dwordx4 v[160:161], off
	s_waitcnt vmcnt(8)
	s_waitcnt lgkmcnt(0)
	s_barrier
	s_setprio 1
	s_waitcnt lgkmcnt(0)
	v_mfma_f32_16x16x32_bf16 v[60:63], v[156:159], v[206:209], v[60:63]
	v_mfma_f32_16x16x32_bf16 v[52:55], v[170:173], v[206:209], v[52:55]
	v_mfma_f32_16x16x32_bf16 v[44:47], v[156:159], v[214:217], v[44:47]
	v_mfma_f32_16x16x32_bf16 v[36:39], v[170:173], v[214:217], v[36:39]
	v_mfma_f32_16x16x32_bf16 v[28:31], v[156:159], v[222:225], v[28:31]
	v_mfma_f32_16x16x32_bf16 v[20:23], v[170:173], v[222:225], v[20:23]
	v_mfma_f32_16x16x32_bf16 v[12:15], v[156:159], v[230:233], v[12:15]
	v_mfma_f32_16x16x32_bf16 v[4:7], v[170:173], v[230:233], v[4:7]
	v_mfma_f32_16x16x32_bf16 v[60:63], v[166:169], v[210:213], v[60:63]
	v_mfma_f32_16x16x32_bf16 v[52:55], v[182:185], v[210:213], v[52:55]
	v_mfma_f32_16x16x32_bf16 v[44:47], v[166:169], v[218:221], v[44:47]
	v_mfma_f32_16x16x32_bf16 v[36:39], v[182:185], v[218:221], v[36:39]
	v_mfma_f32_16x16x32_bf16 v[28:31], v[166:169], v[226:229], v[28:31]
	v_mfma_f32_16x16x32_bf16 v[20:23], v[182:185], v[226:229], v[20:23]
	v_mfma_f32_16x16x32_bf16 v[12:15], v[166:169], v[234:237], v[12:15]
	v_mfma_f32_16x16x32_bf16 v[4:7], v[182:185], v[234:237], v[4:7]
	v_mfma_f32_16x16x32_bf16 v[56:59], v[186:189], v[206:209], v[56:59]
	v_mfma_f32_16x16x32_bf16 v[48:51], v[198:201], v[206:209], v[48:51]
	v_mfma_f32_16x16x32_bf16 v[40:43], v[186:189], v[214:217], v[40:43]
	v_mfma_f32_16x16x32_bf16 v[32:35], v[198:201], v[214:217], v[32:35]
	v_mfma_f32_16x16x32_bf16 v[24:27], v[186:189], v[222:225], v[24:27]
	v_mfma_f32_16x16x32_bf16 v[16:19], v[198:201], v[222:225], v[16:19]
	v_mfma_f32_16x16x32_bf16 v[8:11], v[186:189], v[230:233], v[8:11]
	v_mfma_f32_16x16x32_bf16 v[0:3], v[198:201], v[230:233], v[0:3]
	v_mfma_f32_16x16x32_bf16 v[56:59], v[194:197], v[210:213], v[56:59]
	v_mfma_f32_16x16x32_bf16 v[48:51], v[202:205], v[210:213], v[48:51]
	v_mfma_f32_16x16x32_bf16 v[40:43], v[194:197], v[218:221], v[40:43]
	v_mfma_f32_16x16x32_bf16 v[32:35], v[202:205], v[218:221], v[32:35]
	v_mfma_f32_16x16x32_bf16 v[24:27], v[194:197], v[226:229], v[24:27]
	v_mfma_f32_16x16x32_bf16 v[16:19], v[202:205], v[226:229], v[16:19]
	v_mfma_f32_16x16x32_bf16 v[8:11], v[194:197], v[234:237], v[8:11]
	v_mfma_f32_16x16x32_bf16 v[0:3], v[202:205], v[234:237], v[0:3]
	s_setprio 0
	s_barrier
	s_add_i32 s94, s94, 2
	s_add_u32 s22, s22, 0x100
	s_addc_u32 s23, s23, 0
	s_add_u32 s65, s65, 0x100
	s_addc_u32 s92, s92, 0
	s_cmp_gt_u32 s94, 29
	s_cbranch_scc0 .LBB0_745
	s_and_b64 vcc, exec, s[42:43]
	s_cbranch_vccz .LBB0_748
	s_barrier
